# v27
# speedup vs baseline: 1.0018x; 1.0018x over previous
.LBB0_269:
	s_add_u32 s26, s24, 0xfff80080
	s_addc_u32 s27, s25, -1
	s_add_i32 s70, 0, 0x10000
	v_add_u32_e32 v148, s70, v154
	ds_read_b128 v[150:153], v148
	ds_read_b128 v[158:161], v148 offset:1024
	ds_read_b128 v[162:165], v148 offset:2048
	ds_read_b128 v[166:169], v148 offset:3072
	s_cmp_eq_u32 s69, 28
	s_cselect_b32 s29, s7, s27
	s_cselect_b32 s28, s6, s26
	s_cselect_b32 s27, s23, s17
	s_cselect_b32 s26, s22, s5
	s_add_i32 m0, s58, 0xc000
	ds_read_b128 v[170:173], v156
	ds_read_b128 v[174:177], v156 offset:1024
	ds_read_b128 v[180:183], v156 offset:2048
	ds_read_b128 v[184:187], v156 offset:3072
	ds_read_b128 v[188:191], v156 offset:4096
	ds_read_b128 v[192:195], v156 offset:5120
	ds_read_b128 v[196:199], v156 offset:6144
	ds_read_b128 v[224:227], v156 offset:7168
	global_load_lds_dwordx4 v146, s[24:25]
	s_add_i32 m0, s58, 0xe000
	s_nop 0
	global_load_lds_dwordx4 v144, s[24:25]
	s_waitcnt lgkmcnt(8)
	s_barrier
	s_waitcnt lgkmcnt(0)
	v_mfma_f32_16x16x32_bf16 v[124:127], v[150:153], v[170:173], v[124:127]
	v_mfma_f32_16x16x32_bf16 v[120:123], v[162:165], v[170:173], v[120:123]
	v_mfma_f32_16x16x32_bf16 v[108:111], v[150:153], v[180:183], v[108:111]
	v_mfma_f32_16x16x32_bf16 v[104:107], v[162:165], v[180:183], v[104:107]
	v_mfma_f32_16x16x32_bf16 v[92:95], v[150:153], v[188:191], v[92:95]
	v_mfma_f32_16x16x32_bf16 v[88:91], v[162:165], v[188:191], v[88:91]
	v_mfma_f32_16x16x32_bf16 v[76:79], v[150:153], v[196:199], v[76:79]
	v_mfma_f32_16x16x32_bf16 v[72:75], v[162:165], v[196:199], v[72:75]
	v_mfma_f32_16x16x32_bf16 v[124:127], v[158:161], v[174:177], v[124:127]
	v_mfma_f32_16x16x32_bf16 v[120:123], v[166:169], v[174:177], v[120:123]
	v_mfma_f32_16x16x32_bf16 v[108:111], v[158:161], v[184:187], v[108:111]
	v_mfma_f32_16x16x32_bf16 v[104:107], v[166:169], v[184:187], v[104:107]
	v_mfma_f32_16x16x32_bf16 v[92:95], v[158:161], v[192:195], v[92:95]
	v_mfma_f32_16x16x32_bf16 v[88:91], v[166:169], v[192:195], v[88:91]
	v_mfma_f32_16x16x32_bf16 v[76:79], v[158:161], v[224:227], v[76:79]
	v_mfma_f32_16x16x32_bf16 v[72:75], v[166:169], v[224:227], v[72:75]
	s_barrier
	s_add_i32 s72, 0, 0x14000
	s_add_i32 s70, s70, s57
	v_add_u32_e32 v148, s72, v154
	s_mov_b32 m0, s70
	ds_read_b128 v[228:231], v148
	ds_read_b128 v[232:235], v148 offset:1024
	ds_read_b128 v[236:239], v148 offset:2048
	ds_read_b128 v[240:243], v148 offset:3072
	global_load_lds_dwordx4 v130, s[26:27]
	s_add_i32 m0, s70, 0x2000
	s_nop 0
	global_load_lds_dwordx4 v134, s[26:27]
	s_barrier
	s_waitcnt lgkmcnt(0)
	v_mfma_f32_16x16x32_bf16 v[116:119], v[228:231], v[170:173], v[116:119]
	v_mfma_f32_16x16x32_bf16 v[112:115], v[236:239], v[170:173], v[112:115]
	v_mfma_f32_16x16x32_bf16 v[100:103], v[228:231], v[180:183], v[100:103]
	v_mfma_f32_16x16x32_bf16 v[96:99], v[236:239], v[180:183], v[96:99]
	v_mfma_f32_16x16x32_bf16 v[84:87], v[228:231], v[188:191], v[84:87]
	v_mfma_f32_16x16x32_bf16 v[80:83], v[236:239], v[188:191], v[80:83]
	v_mfma_f32_16x16x32_bf16 v[68:71], v[228:231], v[196:199], v[68:71]
	v_mfma_f32_16x16x32_bf16 v[64:67], v[236:239], v[196:199], v[64:67]
	v_mfma_f32_16x16x32_bf16 v[116:119], v[232:235], v[174:177], v[116:119]
	v_mfma_f32_16x16x32_bf16 v[112:115], v[240:243], v[174:177], v[112:115]
	v_mfma_f32_16x16x32_bf16 v[100:103], v[232:235], v[184:187], v[100:103]
	v_mfma_f32_16x16x32_bf16 v[96:99], v[240:243], v[184:187], v[96:99]
	v_mfma_f32_16x16x32_bf16 v[84:87], v[232:235], v[192:195], v[84:87]
	v_mfma_f32_16x16x32_bf16 v[80:83], v[240:243], v[192:195], v[80:83]
	v_mfma_f32_16x16x32_bf16 v[68:71], v[232:235], v[224:227], v[68:71]
	v_mfma_f32_16x16x32_bf16 v[64:67], v[240:243], v[224:227], v[64:67]
	s_mov_b32 m0, s58
	s_mov_b64 s[100:101], s[28:29]
	s_barrier
	ds_read_b128 v[170:173], v156 offset:16384
	ds_read_b128 v[174:177], v156 offset:17408
	ds_read_b128 v[180:183], v156 offset:18432
	ds_read_b128 v[184:187], v156 offset:19456
	ds_read_b128 v[188:191], v156 offset:20480
	ds_read_b128 v[192:195], v156 offset:21504
	ds_read_b128 v[196:199], v156 offset:22528
	ds_read_b128 v[224:227], v156 offset:23552
	global_load_lds_dwordx4 v128, s[28:29]
	s_mov_b32 m0, s59
	s_mov_b64 s[100:101], s[28:29]
	global_load_lds_dwordx4 v132, s[28:29]
	s_barrier
	s_waitcnt lgkmcnt(0)
	v_mfma_f32_16x16x32_bf16 v[60:63], v[150:153], v[170:173], v[60:63]
	v_mfma_f32_16x16x32_bf16 v[56:59], v[162:165], v[170:173], v[56:59]
	v_mfma_f32_16x16x32_bf16 v[44:47], v[150:153], v[180:183], v[44:47]
	v_mfma_f32_16x16x32_bf16 v[40:43], v[162:165], v[180:183], v[40:43]
	v_mfma_f32_16x16x32_bf16 v[28:31], v[150:153], v[188:191], v[28:31]
	v_mfma_f32_16x16x32_bf16 v[24:27], v[162:165], v[188:191], v[24:27]
	v_mfma_f32_16x16x32_bf16 v[12:15], v[150:153], v[196:199], v[12:15]
	v_mfma_f32_16x16x32_bf16 v[8:11], v[162:165], v[196:199], v[8:11]
	v_mfma_f32_16x16x32_bf16 v[60:63], v[158:161], v[174:177], v[60:63]
	v_mfma_f32_16x16x32_bf16 v[56:59], v[166:169], v[174:177], v[56:59]
	v_mfma_f32_16x16x32_bf16 v[44:47], v[158:161], v[184:187], v[44:47]
	v_mfma_f32_16x16x32_bf16 v[40:43], v[166:169], v[184:187], v[40:43]
	v_mfma_f32_16x16x32_bf16 v[28:31], v[158:161], v[192:195], v[28:31]
	v_mfma_f32_16x16x32_bf16 v[24:27], v[166:169], v[192:195], v[24:27]
	v_mfma_f32_16x16x32_bf16 v[12:15], v[158:161], v[224:227], v[12:15]
	v_mfma_f32_16x16x32_bf16 v[8:11], v[166:169], v[224:227], v[8:11]
	s_barrier
	s_add_u32 s70, s26, 0x80000
	s_addc_u32 s71, s27, 0
	s_add_i32 s72, s72, s57
	s_mov_b32 m0, s72
	s_nop 0
	global_load_lds_dwordx4 v130, s[70:71]
	s_add_i32 m0, s72, 0x2000
	s_nop 0
	global_load_lds_dwordx4 v134, s[70:71]
	s_waitcnt vmcnt(6)
	s_barrier
	v_mfma_f32_16x16x32_bf16 v[52:55], v[228:231], v[170:173], v[52:55]
	v_mfma_f32_16x16x32_bf16 v[48:51], v[236:239], v[170:173], v[48:51]
	v_mfma_f32_16x16x32_bf16 v[36:39], v[228:231], v[180:183], v[36:39]
	v_mfma_f32_16x16x32_bf16 v[32:35], v[236:239], v[180:183], v[32:35]
	v_mfma_f32_16x16x32_bf16 v[20:23], v[228:231], v[188:191], v[20:23]
	v_mfma_f32_16x16x32_bf16 v[16:19], v[236:239], v[188:191], v[16:19]
	v_mfma_f32_16x16x32_bf16 v[4:7], v[228:231], v[196:199], v[4:7]
	v_mfma_f32_16x16x32_bf16 v[0:3], v[236:239], v[196:199], v[0:3]
	v_mfma_f32_16x16x32_bf16 v[52:55], v[232:235], v[174:177], v[52:55]
	v_mfma_f32_16x16x32_bf16 v[48:51], v[240:243], v[174:177], v[48:51]
	v_mfma_f32_16x16x32_bf16 v[36:39], v[232:235], v[184:187], v[36:39]
	v_mfma_f32_16x16x32_bf16 v[32:35], v[240:243], v[184:187], v[32:35]
	v_mfma_f32_16x16x32_bf16 v[20:23], v[232:235], v[192:195], v[20:23]
	v_mfma_f32_16x16x32_bf16 v[16:19], v[240:243], v[192:195], v[16:19]
	v_mfma_f32_16x16x32_bf16 v[4:7], v[232:235], v[224:227], v[4:7]
	v_mfma_f32_16x16x32_bf16 v[0:3], v[240:243], v[224:227], v[0:3]
	s_add_i32 s70, 0, 0x18000
	v_add_u32_e32 v148, s70, v154
	s_barrier
	ds_read_b128 v[150:153], v148
	ds_read_b128 v[158:161], v148 offset:1024
	ds_read_b128 v[162:165], v148 offset:2048
	ds_read_b128 v[166:169], v148 offset:3072
	s_add_u32 s28, s28, 0x80000
	s_addc_u32 s29, s29, 0
	s_mov_b32 m0, s60
	ds_read_b128 v[170:173], v156 offset:32768
	ds_read_b128 v[174:177], v156 offset:33792
	ds_read_b128 v[180:183], v156 offset:34816
	ds_read_b128 v[184:187], v156 offset:35840
	ds_read_b128 v[188:191], v156 offset:36864
	ds_read_b128 v[192:195], v156 offset:37888
	ds_read_b128 v[196:199], v156 offset:38912
	ds_read_b128 v[224:227], v156 offset:39936
	global_load_lds_dwordx4 v128, s[28:29]
	s_mov_b32 m0, s61
	s_nop 0
	global_load_lds_dwordx4 v132, s[28:29]
	s_waitcnt lgkmcnt(8)
	s_barrier
	s_waitcnt lgkmcnt(0)
	v_mfma_f32_16x16x32_bf16 v[124:127], v[150:153], v[170:173], v[124:127]
	v_mfma_f32_16x16x32_bf16 v[120:123], v[162:165], v[170:173], v[120:123]
	v_mfma_f32_16x16x32_bf16 v[108:111], v[150:153], v[180:183], v[108:111]
	v_mfma_f32_16x16x32_bf16 v[104:107], v[162:165], v[180:183], v[104:107]
	v_mfma_f32_16x16x32_bf16 v[92:95], v[150:153], v[188:191], v[92:95]
	v_mfma_f32_16x16x32_bf16 v[88:91], v[162:165], v[188:191], v[88:91]
	v_mfma_f32_16x16x32_bf16 v[76:79], v[150:153], v[196:199], v[76:79]
	v_mfma_f32_16x16x32_bf16 v[72:75], v[162:165], v[196:199], v[72:75]
	v_mfma_f32_16x16x32_bf16 v[124:127], v[158:161], v[174:177], v[124:127]
	v_mfma_f32_16x16x32_bf16 v[120:123], v[166:169], v[174:177], v[120:123]
	v_mfma_f32_16x16x32_bf16 v[108:111], v[158:161], v[184:187], v[108:111]
	v_mfma_f32_16x16x32_bf16 v[104:107], v[166:169], v[184:187], v[104:107]
	v_mfma_f32_16x16x32_bf16 v[92:95], v[158:161], v[192:195], v[92:95]
	v_mfma_f32_16x16x32_bf16 v[88:91], v[166:169], v[192:195], v[88:91]
	v_mfma_f32_16x16x32_bf16 v[76:79], v[158:161], v[224:227], v[76:79]
	v_mfma_f32_16x16x32_bf16 v[72:75], v[166:169], v[224:227], v[72:75]
	s_barrier
	s_add_i32 s28, 0, 0x1c000
	s_add_i32 s29, s70, s57
	v_add_u32_e32 v148, s28, v154
	s_add_i32 m0, s29, 0xffffff80
	ds_read_b128 v[228:231], v148
	ds_read_b128 v[232:235], v148 offset:1024
	ds_read_b128 v[236:239], v148 offset:2048
	ds_read_b128 v[240:243], v148 offset:3072
	global_load_lds_dwordx4 v130, s[26:27] offset:128
	s_add_i32 m0, s29, 0x1f80
	s_nop 0
	global_load_lds_dwordx4 v134, s[26:27] offset:128
	s_barrier
	s_waitcnt lgkmcnt(0)
	v_mfma_f32_16x16x32_bf16 v[116:119], v[228:231], v[170:173], v[116:119]
	v_mfma_f32_16x16x32_bf16 v[112:115], v[236:239], v[170:173], v[112:115]
	v_mfma_f32_16x16x32_bf16 v[100:103], v[228:231], v[180:183], v[100:103]
	v_mfma_f32_16x16x32_bf16 v[96:99], v[236:239], v[180:183], v[96:99]
	v_mfma_f32_16x16x32_bf16 v[84:87], v[228:231], v[188:191], v[84:87]
	v_mfma_f32_16x16x32_bf16 v[80:83], v[236:239], v[188:191], v[80:83]
	v_mfma_f32_16x16x32_bf16 v[68:71], v[228:231], v[196:199], v[68:71]
	v_mfma_f32_16x16x32_bf16 v[64:67], v[236:239], v[196:199], v[64:67]
	v_mfma_f32_16x16x32_bf16 v[116:119], v[232:235], v[174:177], v[116:119]
	v_mfma_f32_16x16x32_bf16 v[112:115], v[240:243], v[174:177], v[112:115]
	v_mfma_f32_16x16x32_bf16 v[100:103], v[232:235], v[184:187], v[100:103]
	v_mfma_f32_16x16x32_bf16 v[96:99], v[240:243], v[184:187], v[96:99]
	v_mfma_f32_16x16x32_bf16 v[84:87], v[232:235], v[192:195], v[84:87]
	v_mfma_f32_16x16x32_bf16 v[80:83], v[240:243], v[192:195], v[80:83]
	v_mfma_f32_16x16x32_bf16 v[68:71], v[232:235], v[224:227], v[68:71]
	v_mfma_f32_16x16x32_bf16 v[64:67], v[240:243], v[224:227], v[64:67]
	s_add_i32 m0, s62, 0xffffff80
	s_barrier
	ds_read_b128 v[170:173], v156 offset:49152
	ds_read_b128 v[174:177], v156 offset:50176
	ds_read_b128 v[180:183], v156 offset:51200
	ds_read_b128 v[184:187], v156 offset:52224
	ds_read_b128 v[188:191], v156 offset:53248
	ds_read_b128 v[192:195], v156 offset:54272
	ds_read_b128 v[196:199], v156 offset:55296
	ds_read_b128 v[224:227], v156 offset:56320
	global_load_lds_dwordx4 v128, s[100:101] offset:128
	s_add_i32 m0, s63, 0xffffff80
	s_nop 0
	global_load_lds_dwordx4 v132, s[100:101] offset:128
	s_barrier
	s_waitcnt lgkmcnt(0)
	v_mfma_f32_16x16x32_bf16 v[60:63], v[150:153], v[170:173], v[60:63]
	v_mfma_f32_16x16x32_bf16 v[56:59], v[162:165], v[170:173], v[56:59]
	v_mfma_f32_16x16x32_bf16 v[44:47], v[150:153], v[180:183], v[44:47]
	v_mfma_f32_16x16x32_bf16 v[40:43], v[162:165], v[180:183], v[40:43]
	v_mfma_f32_16x16x32_bf16 v[28:31], v[150:153], v[188:191], v[28:31]
	v_mfma_f32_16x16x32_bf16 v[24:27], v[162:165], v[188:191], v[24:27]
	v_mfma_f32_16x16x32_bf16 v[12:15], v[150:153], v[196:199], v[12:15]
	v_mfma_f32_16x16x32_bf16 v[8:11], v[162:165], v[196:199], v[8:11]
	v_mfma_f32_16x16x32_bf16 v[60:63], v[158:161], v[174:177], v[60:63]
	v_mfma_f32_16x16x32_bf16 v[56:59], v[166:169], v[174:177], v[56:59]
	v_mfma_f32_16x16x32_bf16 v[44:47], v[158:161], v[184:187], v[44:47]
	v_mfma_f32_16x16x32_bf16 v[40:43], v[166:169], v[184:187], v[40:43]
	v_mfma_f32_16x16x32_bf16 v[28:31], v[158:161], v[192:195], v[28:31]
	v_mfma_f32_16x16x32_bf16 v[24:27], v[166:169], v[192:195], v[24:27]
	v_mfma_f32_16x16x32_bf16 v[12:15], v[158:161], v[224:227], v[12:15]
	v_mfma_f32_16x16x32_bf16 v[8:11], v[166:169], v[224:227], v[8:11]
	s_barrier
	s_add_u32 s26, s26, 0x80080
	s_addc_u32 s27, s27, 0
	s_add_i32 s28, s28, s57
	s_mov_b32 m0, s28
	s_nop 0
	global_load_lds_dwordx4 v130, s[26:27]
	s_add_i32 m0, s28, 0x2000
	s_nop 0
	global_load_lds_dwordx4 v134, s[26:27]
	s_waitcnt vmcnt(6)
	s_barrier
	v_mfma_f32_16x16x32_bf16 v[52:55], v[228:231], v[170:173], v[52:55]
	v_mfma_f32_16x16x32_bf16 v[48:51], v[236:239], v[170:173], v[48:51]
	v_mfma_f32_16x16x32_bf16 v[36:39], v[228:231], v[180:183], v[36:39]
	v_mfma_f32_16x16x32_bf16 v[32:35], v[236:239], v[180:183], v[32:35]
	v_mfma_f32_16x16x32_bf16 v[20:23], v[228:231], v[188:191], v[20:23]
	v_mfma_f32_16x16x32_bf16 v[16:19], v[236:239], v[188:191], v[16:19]
	v_mfma_f32_16x16x32_bf16 v[4:7], v[228:231], v[196:199], v[4:7]
	v_mfma_f32_16x16x32_bf16 v[0:3], v[236:239], v[196:199], v[0:3]
	v_mfma_f32_16x16x32_bf16 v[52:55], v[232:235], v[174:177], v[52:55]
	v_mfma_f32_16x16x32_bf16 v[48:51], v[240:243], v[174:177], v[48:51]
	v_mfma_f32_16x16x32_bf16 v[36:39], v[232:235], v[184:187], v[36:39]
	v_mfma_f32_16x16x32_bf16 v[32:35], v[240:243], v[184:187], v[32:35]
	v_mfma_f32_16x16x32_bf16 v[20:23], v[232:235], v[192:195], v[20:23]
	v_mfma_f32_16x16x32_bf16 v[16:19], v[240:243], v[192:195], v[16:19]
	v_mfma_f32_16x16x32_bf16 v[4:7], v[232:235], v[224:227], v[4:7]
	v_mfma_f32_16x16x32_bf16 v[0:3], v[240:243], v[224:227], v[0:3]
	s_add_i32 s69, s69, 2
	s_add_u32 s5, s5, 0x100
	s_addc_u32 s17, s17, 0
	s_add_u32 s24, s24, 0x100
	s_addc_u32 s25, s25, 0
	s_cmp_gt_u32 s69, 29
	s_barrier
	s_cbranch_scc0 .LBB0_269
	s_lshl_b32 s5, s68, 8
	v_lshl_add_u32 v158, s4, 8, v137
	v_or_b32_e32 v148, s5, v136
	s_addk_i32 s5, 0xf000
	s_lshr_b32 s4, s5, 2
	v_and_b32_e32 v159, 0xffffff80, v158
	s_and_b32 s22, s4, 0x3ffffe00
	v_add_u32_e32 v160, v159, v155
	v_add_u32_e32 v150, s22, v160
	s_lshl_b32 s17, s68, 9
	v_ashrrev_i32_e32 v151, 31, v150
	v_lshlrev_b64 v[152:153], 13, v[150:151]
	v_add_u32_e32 v150, s17, v160
	v_ashrrev_i32_e32 v151, 31, v150
	v_cmp_ne_u32_e64 s[6:7], 0, v149
	s_movk_i32 s4, 0xfff
	v_lshlrev_b64 v[150:151], 10, v[150:151]
	s_and_b64 vcc, exec, s[6:7]
	v_cmp_lt_i32_e64 s[4:5], s4, v148
	v_cvt_pk_bf16_f32 v124, v124, v125
	v_cvt_pk_bf16_f32 v125, v126, v127
	v_cvt_pk_bf16_f32 v126, v120, v121
	v_cvt_pk_bf16_f32 v127, v122, v123
	s_cbranch_vccz .LBB0_290
	s_and_saveexec_b64 s[24:25], s[4:5]
	s_xor_b64 s[4:5], exec, s[24:25]
	v_and_b32_e32 v122, 0x778, v148
	v_lshl_add_u64 v[120:121], v[138:139], 0, v[152:153]
	v_lshlrev_b32_e32 v178, 1, v122
	v_lshl_add_u64 v[122:123], v[120:121], 0, v[178:179]
	s_andn2_saveexec_b64 s[4:5], s[4:5]
	v_lshl_add_u64 v[122:123], v[142:143], 0, v[150:151]
	s_or_b64 exec, exec, s[4:5]
	s_movk_i32 s4, 0x1a00
	v_mad_i64_i32 v[120:121], s[4:5], v158, s4, 0
	s_cbranch_execnz .LBB0_277

.LBB0_935:
	s_add_u32 s12, s10, 0xf4c00080
	s_addc_u32 s13, s11, -1
	s_cmp_lg_u32 s28, 60
	s_cselect_b32 s12, s12, 0
	s_cselect_b32 s13, s13, 0
	s_add_u32 s14, s6, s12
	s_addc_u32 s15, s7, s13
	s_add_i32 s29, 0, 0x10000
	v_add_u32_e32 v150, s29, v140
	ds_read_b128 v[142:145], v150
	ds_read_b128 v[146:149], v150 offset:1024
	ds_read_b128 v[154:157], v150 offset:2048
	ds_read_b128 v[158:161], v150 offset:3072
	s_add_u32 s12, s8, s12
	s_addc_u32 s13, s9, s13
	v_lshl_add_u64 v[150:151], v[136:137], 0, s[10:11]
	s_add_i32 m0, s22, 0xc000
	ds_read_b128 v[162:165], v141
	ds_read_b128 v[166:169], v141 offset:1024
	ds_read_b128 v[170:173], v141 offset:2048
	ds_read_b128 v[174:177], v141 offset:3072
	ds_read_b128 v[180:183], v141 offset:4096
	ds_read_b128 v[184:187], v141 offset:5120
	ds_read_b128 v[188:191], v141 offset:6144
	ds_read_b128 v[192:195], v141 offset:7168
	global_load_lds_dwordx4 v[150:151], off
	v_lshl_add_u64 v[150:151], v[134:135], 0, s[10:11]
	s_add_i32 m0, s22, 0xe000
	s_nop 0
	global_load_lds_dwordx4 v[150:151], off
	s_waitcnt lgkmcnt(8)
	s_barrier
	s_waitcnt lgkmcnt(0)
	v_mfma_f32_16x16x32_bf16 v[124:127], v[142:145], v[162:165], v[124:127]
	v_mfma_f32_16x16x32_bf16 v[120:123], v[154:157], v[162:165], v[120:123]
	v_mfma_f32_16x16x32_bf16 v[116:119], v[142:145], v[170:173], v[116:119]
	v_mfma_f32_16x16x32_bf16 v[108:111], v[154:157], v[170:173], v[108:111]
	v_mfma_f32_16x16x32_bf16 v[100:103], v[142:145], v[180:183], v[100:103]
	v_mfma_f32_16x16x32_bf16 v[92:95], v[154:157], v[180:183], v[92:95]
	v_mfma_f32_16x16x32_bf16 v[84:87], v[142:145], v[188:191], v[84:87]
	v_mfma_f32_16x16x32_bf16 v[76:79], v[154:157], v[188:191], v[76:79]
	v_mfma_f32_16x16x32_bf16 v[124:127], v[146:149], v[166:169], v[124:127]
	v_mfma_f32_16x16x32_bf16 v[120:123], v[158:161], v[166:169], v[120:123]
	v_mfma_f32_16x16x32_bf16 v[116:119], v[146:149], v[174:177], v[116:119]
	v_mfma_f32_16x16x32_bf16 v[108:111], v[158:161], v[174:177], v[108:111]
	v_mfma_f32_16x16x32_bf16 v[100:103], v[146:149], v[184:187], v[100:103]
	v_mfma_f32_16x16x32_bf16 v[92:95], v[158:161], v[184:187], v[92:95]
	v_mfma_f32_16x16x32_bf16 v[84:87], v[146:149], v[192:195], v[84:87]
	v_mfma_f32_16x16x32_bf16 v[76:79], v[158:161], v[192:195], v[76:79]
	s_barrier
	s_add_i32 s35, 0, 0x14000
	v_add_u32_e32 v150, s35, v140
	s_add_i32 s29, s29, s16
	ds_read_b128 v[196:199], v150
	ds_read_b128 v[224:227], v150 offset:1024
	ds_read_b128 v[228:231], v150 offset:2048
	ds_read_b128 v[232:235], v150 offset:3072
	s_mov_b32 m0, s29
	s_nop 0
	global_load_lds_dwordx4 v178, s[12:13]
	s_add_i32 m0, s29, 0x2000
	s_nop 0
	global_load_lds_dwordx4 v128, s[12:13]
	s_barrier
	s_waitcnt lgkmcnt(0)
	v_mfma_f32_16x16x32_bf16 v[112:115], v[196:199], v[162:165], v[112:115]
	v_mfma_f32_16x16x32_bf16 v[104:107], v[228:231], v[162:165], v[104:107]
	v_mfma_f32_16x16x32_bf16 v[96:99], v[196:199], v[170:173], v[96:99]
	v_mfma_f32_16x16x32_bf16 v[88:91], v[228:231], v[170:173], v[88:91]
	v_mfma_f32_16x16x32_bf16 v[80:83], v[196:199], v[180:183], v[80:83]
	v_mfma_f32_16x16x32_bf16 v[72:75], v[228:231], v[180:183], v[72:75]
	v_mfma_f32_16x16x32_bf16 v[68:71], v[196:199], v[188:191], v[68:71]
	v_mfma_f32_16x16x32_bf16 v[64:67], v[228:231], v[188:191], v[64:67]
	v_mfma_f32_16x16x32_bf16 v[112:115], v[224:227], v[166:169], v[112:115]
	v_mfma_f32_16x16x32_bf16 v[104:107], v[232:235], v[166:169], v[104:107]
	v_mfma_f32_16x16x32_bf16 v[96:99], v[224:227], v[174:177], v[96:99]
	v_mfma_f32_16x16x32_bf16 v[88:91], v[232:235], v[174:177], v[88:91]
	v_mfma_f32_16x16x32_bf16 v[80:83], v[224:227], v[184:187], v[80:83]
	v_mfma_f32_16x16x32_bf16 v[72:75], v[232:235], v[184:187], v[72:75]
	v_mfma_f32_16x16x32_bf16 v[68:71], v[224:227], v[192:195], v[68:71]
	v_mfma_f32_16x16x32_bf16 v[64:67], v[232:235], v[192:195], v[64:67]
	s_mov_b32 m0, s22
	s_mov_b64 s[100:101], s[14:15]
	s_barrier
	ds_read_b128 v[162:165], v141 offset:16384
	ds_read_b128 v[166:169], v141 offset:17408
	ds_read_b128 v[170:173], v141 offset:18432
	ds_read_b128 v[174:177], v141 offset:19456
	ds_read_b128 v[180:183], v141 offset:20480
	ds_read_b128 v[184:187], v141 offset:21504
	ds_read_b128 v[188:191], v141 offset:22528
	ds_read_b128 v[192:195], v141 offset:23552
	global_load_lds_dwordx4 v132, s[14:15]
	s_mov_b32 m0, s23
	s_mov_b64 s[100:101], s[14:15]
	global_load_lds_dwordx4 v130, s[14:15]
	s_barrier
	s_waitcnt lgkmcnt(0)
	v_mfma_f32_16x16x32_bf16 v[60:63], v[142:145], v[162:165], v[60:63]
	v_mfma_f32_16x16x32_bf16 v[56:59], v[154:157], v[162:165], v[56:59]
	v_mfma_f32_16x16x32_bf16 v[52:55], v[142:145], v[170:173], v[52:55]
	v_mfma_f32_16x16x32_bf16 v[44:47], v[154:157], v[170:173], v[44:47]
	v_mfma_f32_16x16x32_bf16 v[36:39], v[142:145], v[180:183], v[36:39]
	v_mfma_f32_16x16x32_bf16 v[28:31], v[154:157], v[180:183], v[28:31]
	v_mfma_f32_16x16x32_bf16 v[20:23], v[142:145], v[188:191], v[20:23]
	v_mfma_f32_16x16x32_bf16 v[12:15], v[154:157], v[188:191], v[12:15]
	v_mfma_f32_16x16x32_bf16 v[60:63], v[146:149], v[166:169], v[60:63]
	v_mfma_f32_16x16x32_bf16 v[56:59], v[158:161], v[166:169], v[56:59]
	v_mfma_f32_16x16x32_bf16 v[52:55], v[146:149], v[174:177], v[52:55]
	v_mfma_f32_16x16x32_bf16 v[44:47], v[158:161], v[174:177], v[44:47]
	v_mfma_f32_16x16x32_bf16 v[36:39], v[146:149], v[184:187], v[36:39]
	v_mfma_f32_16x16x32_bf16 v[28:31], v[158:161], v[184:187], v[28:31]
	v_mfma_f32_16x16x32_bf16 v[20:23], v[146:149], v[192:195], v[20:23]
	v_mfma_f32_16x16x32_bf16 v[12:15], v[158:161], v[192:195], v[12:15]
	s_barrier
	s_add_u32 s30, s12, 0x100000
	s_addc_u32 s31, s13, 0
	s_add_i32 s29, s35, s16
	s_mov_b32 m0, s29
	s_nop 0
	global_load_lds_dwordx4 v178, s[30:31]
	s_add_i32 m0, s29, 0x2000
	s_nop 0
	global_load_lds_dwordx4 v128, s[30:31]
	s_waitcnt vmcnt(6)
	s_barrier
	v_mfma_f32_16x16x32_bf16 v[48:51], v[196:199], v[162:165], v[48:51]
	v_mfma_f32_16x16x32_bf16 v[40:43], v[228:231], v[162:165], v[40:43]
	v_mfma_f32_16x16x32_bf16 v[32:35], v[196:199], v[170:173], v[32:35]
	v_mfma_f32_16x16x32_bf16 v[24:27], v[228:231], v[170:173], v[24:27]
	v_mfma_f32_16x16x32_bf16 v[16:19], v[196:199], v[180:183], v[16:19]
	v_mfma_f32_16x16x32_bf16 v[8:11], v[228:231], v[180:183], v[8:11]
	v_mfma_f32_16x16x32_bf16 v[4:7], v[196:199], v[188:191], v[4:7]
	v_mfma_f32_16x16x32_bf16 v[0:3], v[228:231], v[188:191], v[0:3]
	v_mfma_f32_16x16x32_bf16 v[48:51], v[224:227], v[166:169], v[48:51]
	v_mfma_f32_16x16x32_bf16 v[40:43], v[232:235], v[166:169], v[40:43]
	v_mfma_f32_16x16x32_bf16 v[32:35], v[224:227], v[174:177], v[32:35]
	v_mfma_f32_16x16x32_bf16 v[24:27], v[232:235], v[174:177], v[24:27]
	v_mfma_f32_16x16x32_bf16 v[16:19], v[224:227], v[184:187], v[16:19]
	v_mfma_f32_16x16x32_bf16 v[8:11], v[232:235], v[184:187], v[8:11]
	v_mfma_f32_16x16x32_bf16 v[4:7], v[224:227], v[192:195], v[4:7]
	v_mfma_f32_16x16x32_bf16 v[0:3], v[232:235], v[192:195], v[0:3]
	s_add_i32 s29, 0, 0x18000
	v_add_u32_e32 v153, s29, v140
	s_barrier
	ds_read_b128 v[142:145], v153
	ds_read_b128 v[146:149], v153 offset:1024
	ds_read_b128 v[154:157], v153 offset:2048
	ds_read_b128 v[158:161], v153 offset:3072
	s_add_u32 s14, s14, 0x100000
	s_addc_u32 s15, s15, 0
	s_mov_b32 m0, s24
	ds_read_b128 v[162:165], v141 offset:32768
	ds_read_b128 v[166:169], v141 offset:33792
	ds_read_b128 v[170:173], v141 offset:34816
	ds_read_b128 v[174:177], v141 offset:35840
	ds_read_b128 v[180:183], v141 offset:36864
	ds_read_b128 v[184:187], v141 offset:37888
	ds_read_b128 v[188:191], v141 offset:38912
	ds_read_b128 v[192:195], v141 offset:39936
	global_load_lds_dwordx4 v132, s[14:15]
	s_mov_b32 m0, s25
	s_nop 0
	global_load_lds_dwordx4 v130, s[14:15]
	s_waitcnt lgkmcnt(8)
	s_barrier
	s_waitcnt lgkmcnt(0)
	v_mfma_f32_16x16x32_bf16 v[124:127], v[142:145], v[162:165], v[124:127]
	v_mfma_f32_16x16x32_bf16 v[120:123], v[154:157], v[162:165], v[120:123]
	v_mfma_f32_16x16x32_bf16 v[116:119], v[142:145], v[170:173], v[116:119]
	v_mfma_f32_16x16x32_bf16 v[108:111], v[154:157], v[170:173], v[108:111]
	v_mfma_f32_16x16x32_bf16 v[100:103], v[142:145], v[180:183], v[100:103]
	v_mfma_f32_16x16x32_bf16 v[92:95], v[154:157], v[180:183], v[92:95]
	v_mfma_f32_16x16x32_bf16 v[84:87], v[142:145], v[188:191], v[84:87]
	v_mfma_f32_16x16x32_bf16 v[76:79], v[154:157], v[188:191], v[76:79]
	v_mfma_f32_16x16x32_bf16 v[124:127], v[146:149], v[166:169], v[124:127]
	v_mfma_f32_16x16x32_bf16 v[120:123], v[158:161], v[166:169], v[120:123]
	v_mfma_f32_16x16x32_bf16 v[116:119], v[146:149], v[174:177], v[116:119]
	v_mfma_f32_16x16x32_bf16 v[108:111], v[158:161], v[174:177], v[108:111]
	v_mfma_f32_16x16x32_bf16 v[100:103], v[146:149], v[184:187], v[100:103]
	v_mfma_f32_16x16x32_bf16 v[92:95], v[158:161], v[184:187], v[92:95]
	v_mfma_f32_16x16x32_bf16 v[84:87], v[146:149], v[192:195], v[84:87]
	v_mfma_f32_16x16x32_bf16 v[76:79], v[158:161], v[192:195], v[76:79]
	s_barrier
	s_add_i32 s14, 0, 0x1c000
	s_add_i32 s15, s29, s16
	v_add_u32_e32 v153, s14, v140
	s_add_i32 m0, s15, 0xffffff80
	ds_read_b128 v[196:199], v153
	ds_read_b128 v[224:227], v153 offset:1024
	ds_read_b128 v[228:231], v153 offset:2048
	ds_read_b128 v[232:235], v153 offset:3072
	global_load_lds_dwordx4 v178, s[12:13] offset:128
	s_add_i32 m0, s15, 0x1f80
	s_nop 0
	global_load_lds_dwordx4 v128, s[12:13] offset:128
	s_barrier
	s_waitcnt lgkmcnt(0)
	v_mfma_f32_16x16x32_bf16 v[112:115], v[196:199], v[162:165], v[112:115]
	v_mfma_f32_16x16x32_bf16 v[104:107], v[228:231], v[162:165], v[104:107]
	v_mfma_f32_16x16x32_bf16 v[96:99], v[196:199], v[170:173], v[96:99]
	v_mfma_f32_16x16x32_bf16 v[88:91], v[228:231], v[170:173], v[88:91]
	v_mfma_f32_16x16x32_bf16 v[80:83], v[196:199], v[180:183], v[80:83]
	v_mfma_f32_16x16x32_bf16 v[72:75], v[228:231], v[180:183], v[72:75]
	v_mfma_f32_16x16x32_bf16 v[68:71], v[196:199], v[188:191], v[68:71]
	v_mfma_f32_16x16x32_bf16 v[64:67], v[228:231], v[188:191], v[64:67]
	v_mfma_f32_16x16x32_bf16 v[112:115], v[224:227], v[166:169], v[112:115]
	v_mfma_f32_16x16x32_bf16 v[104:107], v[232:235], v[166:169], v[104:107]
	v_mfma_f32_16x16x32_bf16 v[96:99], v[224:227], v[174:177], v[96:99]
	v_mfma_f32_16x16x32_bf16 v[88:91], v[232:235], v[174:177], v[88:91]
	v_mfma_f32_16x16x32_bf16 v[80:83], v[224:227], v[184:187], v[80:83]
	v_mfma_f32_16x16x32_bf16 v[72:75], v[232:235], v[184:187], v[72:75]
	v_mfma_f32_16x16x32_bf16 v[68:71], v[224:227], v[192:195], v[68:71]
	v_mfma_f32_16x16x32_bf16 v[64:67], v[232:235], v[192:195], v[64:67]
	s_add_i32 m0, s26, 0xffffff80
	s_barrier
	ds_read_b128 v[162:165], v141 offset:49152
	ds_read_b128 v[166:169], v141 offset:50176
	ds_read_b128 v[170:173], v141 offset:51200
	ds_read_b128 v[174:177], v141 offset:52224
	ds_read_b128 v[180:183], v141 offset:53248
	ds_read_b128 v[184:187], v141 offset:54272
	ds_read_b128 v[188:191], v141 offset:55296
	ds_read_b128 v[192:195], v141 offset:56320
	global_load_lds_dwordx4 v132, s[100:101] offset:128
	s_add_i32 m0, s27, 0xffffff80
	s_nop 0
	global_load_lds_dwordx4 v130, s[100:101] offset:128
	s_barrier
	s_waitcnt lgkmcnt(0)
	v_mfma_f32_16x16x32_bf16 v[60:63], v[142:145], v[162:165], v[60:63]
	v_mfma_f32_16x16x32_bf16 v[56:59], v[154:157], v[162:165], v[56:59]
	v_mfma_f32_16x16x32_bf16 v[52:55], v[142:145], v[170:173], v[52:55]
	v_mfma_f32_16x16x32_bf16 v[44:47], v[154:157], v[170:173], v[44:47]
	v_mfma_f32_16x16x32_bf16 v[36:39], v[142:145], v[180:183], v[36:39]
	v_mfma_f32_16x16x32_bf16 v[28:31], v[154:157], v[180:183], v[28:31]
	v_mfma_f32_16x16x32_bf16 v[20:23], v[142:145], v[188:191], v[20:23]
	v_mfma_f32_16x16x32_bf16 v[12:15], v[154:157], v[188:191], v[12:15]
	v_mfma_f32_16x16x32_bf16 v[60:63], v[146:149], v[166:169], v[60:63]
	v_mfma_f32_16x16x32_bf16 v[56:59], v[158:161], v[166:169], v[56:59]
	v_mfma_f32_16x16x32_bf16 v[52:55], v[146:149], v[174:177], v[52:55]
	v_mfma_f32_16x16x32_bf16 v[44:47], v[158:161], v[174:177], v[44:47]
	v_mfma_f32_16x16x32_bf16 v[36:39], v[146:149], v[184:187], v[36:39]
	v_mfma_f32_16x16x32_bf16 v[28:31], v[158:161], v[184:187], v[28:31]
	v_mfma_f32_16x16x32_bf16 v[20:23], v[146:149], v[192:195], v[20:23]
	v_mfma_f32_16x16x32_bf16 v[12:15], v[158:161], v[192:195], v[12:15]
	s_barrier
	s_add_u32 s12, s12, 0x100080
	s_addc_u32 s13, s13, 0
	s_add_i32 s14, s14, s16
	s_mov_b32 m0, s14
	s_nop 0
	global_load_lds_dwordx4 v178, s[12:13]
	s_add_i32 m0, s14, 0x2000
	s_nop 0
	global_load_lds_dwordx4 v128, s[12:13]
	s_waitcnt vmcnt(6)
	s_barrier
	v_mfma_f32_16x16x32_bf16 v[48:51], v[196:199], v[162:165], v[48:51]
	v_mfma_f32_16x16x32_bf16 v[40:43], v[228:231], v[162:165], v[40:43]
	v_mfma_f32_16x16x32_bf16 v[32:35], v[196:199], v[170:173], v[32:35]
	v_mfma_f32_16x16x32_bf16 v[24:27], v[228:231], v[170:173], v[24:27]
	v_mfma_f32_16x16x32_bf16 v[16:19], v[196:199], v[180:183], v[16:19]
	v_mfma_f32_16x16x32_bf16 v[8:11], v[228:231], v[180:183], v[8:11]
	v_mfma_f32_16x16x32_bf16 v[4:7], v[196:199], v[188:191], v[4:7]
	v_mfma_f32_16x16x32_bf16 v[0:3], v[228:231], v[188:191], v[0:3]
	v_mfma_f32_16x16x32_bf16 v[48:51], v[224:227], v[166:169], v[48:51]
	v_mfma_f32_16x16x32_bf16 v[40:43], v[232:235], v[166:169], v[40:43]
	v_mfma_f32_16x16x32_bf16 v[32:35], v[224:227], v[174:177], v[32:35]
	v_mfma_f32_16x16x32_bf16 v[24:27], v[232:235], v[174:177], v[24:27]
	v_mfma_f32_16x16x32_bf16 v[16:19], v[224:227], v[184:187], v[16:19]
	v_mfma_f32_16x16x32_bf16 v[8:11], v[232:235], v[184:187], v[8:11]
	v_mfma_f32_16x16x32_bf16 v[4:7], v[224:227], v[192:195], v[4:7]
	v_mfma_f32_16x16x32_bf16 v[0:3], v[232:235], v[192:195], v[0:3]
	s_add_i32 s28, s28, 2
	s_add_u32 s10, s10, 0x100
	s_addc_u32 s11, s11, 0
	s_cmp_gt_u32 s28, 61
	s_barrier
	s_cbranch_scc0 .LBB0_935
	v_readlane_b32 s6, v253, 51
	s_or_b32 s6, s17, s6
	v_cvt_pk_bf16_f32 v124, v124, v125
	v_cvt_pk_bf16_f32 v125, v126, v127
	v_cvt_pk_bf16_f32 v126, v120, v121
	v_cvt_pk_bf16_f32 v127, v122, v123
	s_nop 0
	v_or_b32_e32 v130, s6, v139
	v_readlane_b32 s6, v253, 44
	v_lshlrev_b32_e32 v178, 1, v130
	s_nop 0
	v_add_u32_e32 v131, s6, v138
	v_add_u32_e32 v128, 0x1000, v131
	v_ashrrev_i32_e32 v129, 31, v128
	v_lshlrev_b64 v[128:129], 12, v[128:129]
	v_lshl_add_u64 v[128:129], s[4:5], 0, v[128:129]
	v_lshl_add_u64 v[128:129], v[128:129], 0, v[178:179]
	global_store_dwordx4 v[128:129], v[124:127], off
	v_cvt_pk_bf16_f32 v112, v112, v113
	v_cvt_pk_bf16_f32 v113, v114, v115
	v_cvt_pk_bf16_f32 v114, v104, v105
	v_add_u32_e32 v104, 0x1010, v131
	v_ashrrev_i32_e32 v105, 31, v104
	v_lshlrev_b64 v[104:105], 12, v[104:105]
	v_lshl_add_u64 v[104:105], s[4:5], 0, v[104:105]
	v_cvt_pk_bf16_f32 v115, v106, v107
	global_store_dwordx4 v[128:129], v[112:115], off offset:256
	v_readlane_b32 s6, v255, 8
	s_nop 0
	v_lshl_add_u64 v[112:113], v[104:105], 0, v[178:179]
	v_cvt_pk_bf16_f32 v104, v116, v117
	v_cvt_pk_bf16_f32 v105, v118, v119
	v_cvt_pk_bf16_f32 v106, v108, v109
	v_cvt_pk_bf16_f32 v107, v110, v111
	global_store_dwordx4 v[112:113], v[104:107], off
	v_cvt_pk_bf16_f32 v96, v96, v97
	v_cvt_pk_bf16_f32 v97, v98, v99
	v_cvt_pk_bf16_f32 v98, v88, v89
	v_add_u32_e32 v88, 0x1020, v131
	v_ashrrev_i32_e32 v89, 31, v88
	v_lshlrev_b64 v[88:89], 12, v[88:89]
	v_lshl_add_u64 v[88:89], s[4:5], 0, v[88:89]
	v_cvt_pk_bf16_f32 v99, v90, v91
	global_store_dwordx4 v[112:113], v[96:99], off offset:256
	s_nop 1
	v_lshl_add_u64 v[96:97], v[88:89], 0, v[178:179]
	v_cvt_pk_bf16_f32 v88, v100, v101
	v_cvt_pk_bf16_f32 v89, v102, v103
	v_cvt_pk_bf16_f32 v90, v92, v93
	v_cvt_pk_bf16_f32 v91, v94, v95
	global_store_dwordx4 v[96:97], v[88:91], off
	v_cvt_pk_bf16_f32 v80, v80, v81
	v_cvt_pk_bf16_f32 v81, v82, v83
	v_cvt_pk_bf16_f32 v82, v72, v73
	v_add_u32_e32 v72, 0x1030, v131
	v_ashrrev_i32_e32 v73, 31, v72
	v_lshlrev_b64 v[72:73], 12, v[72:73]
	v_lshl_add_u64 v[72:73], s[4:5], 0, v[72:73]
	v_cvt_pk_bf16_f32 v83, v74, v75
	global_store_dwordx4 v[96:97], v[80:83], off offset:256
	s_nop 1
	v_lshl_add_u64 v[80:81], v[72:73], 0, v[178:179]
	v_cvt_pk_bf16_f32 v72, v84, v85
	v_cvt_pk_bf16_f32 v73, v86, v87
	v_cvt_pk_bf16_f32 v74, v76, v77
	v_cvt_pk_bf16_f32 v75, v78, v79
	global_store_dwordx4 v[80:81], v[72:75], off
	v_cvt_pk_bf16_f32 v68, v68, v69
	v_cvt_pk_bf16_f32 v69, v70, v71
	v_cvt_pk_bf16_f32 v70, v64, v65
	v_add_u32_e32 v64, 0x1080, v131
	v_ashrrev_i32_e32 v65, 31, v64
	v_lshlrev_b64 v[64:65], 12, v[64:65]
	v_lshl_add_u64 v[64:65], s[4:5], 0, v[64:65]
	v_lshl_add_u64 v[64:65], v[64:65], 0, v[178:179]
	v_cvt_pk_bf16_f32 v71, v66, v67
	global_store_dwordx4 v[80:81], v[68:71], off offset:256
	v_cvt_pk_bf16_f32 v60, v60, v61
	v_cvt_pk_bf16_f32 v61, v62, v63
	v_cvt_pk_bf16_f32 v62, v56, v57
	v_cvt_pk_bf16_f32 v63, v58, v59
	global_store_dwordx4 v[64:65], v[60:63], off
	v_cvt_pk_bf16_f32 v48, v48, v49
	v_cvt_pk_bf16_f32 v49, v50, v51
	v_cvt_pk_bf16_f32 v50, v40, v41
	v_add_u32_e32 v40, 0x1090, v131
	v_ashrrev_i32_e32 v41, 31, v40
	v_lshlrev_b64 v[40:41], 12, v[40:41]
	v_lshl_add_u64 v[40:41], s[4:5], 0, v[40:41]
	v_cvt_pk_bf16_f32 v51, v42, v43
	global_store_dwordx4 v[64:65], v[48:51], off offset:256
	s_nop 1
	v_lshl_add_u64 v[48:49], v[40:41], 0, v[178:179]
	v_cvt_pk_bf16_f32 v40, v52, v53
	v_cvt_pk_bf16_f32 v41, v54, v55
	v_cvt_pk_bf16_f32 v42, v44, v45
	v_cvt_pk_bf16_f32 v43, v46, v47
	global_store_dwordx4 v[48:49], v[40:43], off
	v_cvt_pk_bf16_f32 v32, v32, v33
	v_cvt_pk_bf16_f32 v33, v34, v35
	v_cvt_pk_bf16_f32 v34, v24, v25
	v_add_u32_e32 v24, 0x10a0, v131
	v_ashrrev_i32_e32 v25, 31, v24
	v_lshlrev_b64 v[24:25], 12, v[24:25]
	v_lshl_add_u64 v[24:25], s[4:5], 0, v[24:25]
	v_cvt_pk_bf16_f32 v35, v26, v27
	global_store_dwordx4 v[48:49], v[32:35], off offset:256
	s_nop 1
	v_lshl_add_u64 v[32:33], v[24:25], 0, v[178:179]
	v_cvt_pk_bf16_f32 v24, v36, v37
	v_cvt_pk_bf16_f32 v25, v38, v39
	v_cvt_pk_bf16_f32 v26, v28, v29
	v_cvt_pk_bf16_f32 v27, v30, v31
	global_store_dwordx4 v[32:33], v[24:27], off
	v_cvt_pk_bf16_f32 v16, v16, v17
	v_cvt_pk_bf16_f32 v17, v18, v19
	v_cvt_pk_bf16_f32 v18, v8, v9
	v_add_u32_e32 v8, 0x10b0, v131
	v_ashrrev_i32_e32 v9, 31, v8
	v_lshlrev_b64 v[8:9], 12, v[8:9]
	v_lshl_add_u64 v[8:9], s[4:5], 0, v[8:9]
	v_cvt_pk_bf16_f32 v19, v10, v11
	global_store_dwordx4 v[32:33], v[16:19], off offset:256
	s_nop 1
	v_lshl_add_u64 v[16:17], v[8:9], 0, v[178:179]
	v_cvt_pk_bf16_f32 v8, v20, v21
	v_cvt_pk_bf16_f32 v9, v22, v23
	v_cvt_pk_bf16_f32 v10, v12, v13
	v_cvt_pk_bf16_f32 v11, v14, v15
	global_store_dwordx4 v[16:17], v[8:11], off
	v_cvt_pk_bf16_f32 v4, v4, v5
	v_cvt_pk_bf16_f32 v5, v6, v7
	v_cvt_pk_bf16_f32 v6, v0, v1
	v_cvt_pk_bf16_f32 v7, v2, v3
	global_store_dwordx4 v[16:17], v[4:7], off offset:256
	s_waitcnt vmcnt(0)
	s_cmp_lt_u32 s6, 4
	s_cbranch_scc0 .LBB0_938
	s_barrier

.LBB0_943:
	s_add_u32 s12, s10, 0xf3ce0080
	s_addc_u32 s13, s11, -1
	s_cmp_lg_u32 s20, 4
	s_cselect_b32 s12, s12, 0
	s_cselect_b32 s13, s13, 0
	s_add_u32 s14, s6, s12
	s_addc_u32 s15, s7, s13
	s_add_i32 s21, 0, 0x10000
	v_add_u32_e32 v150, s21, v140
	ds_read_b128 v[142:145], v150
	ds_read_b128 v[146:149], v150 offset:1024
	ds_read_b128 v[154:157], v150 offset:2048
	ds_read_b128 v[158:161], v150 offset:3072
	s_add_u32 s12, s8, s12
	s_addc_u32 s13, s9, s13
	v_lshl_add_u64 v[150:151], v[136:137], 0, s[10:11]
	s_add_i32 m0, s22, 0xc000
	ds_read_b128 v[162:165], v141
	ds_read_b128 v[166:169], v141 offset:1024
	ds_read_b128 v[170:173], v141 offset:2048
	ds_read_b128 v[174:177], v141 offset:3072
	ds_read_b128 v[180:183], v141 offset:4096
	ds_read_b128 v[184:187], v141 offset:5120
	ds_read_b128 v[188:191], v141 offset:6144
	ds_read_b128 v[192:195], v141 offset:7168
	global_load_lds_dwordx4 v[150:151], off
	v_lshl_add_u64 v[150:151], v[134:135], 0, s[10:11]
	s_add_i32 m0, s22, 0xe000
	s_nop 0
	global_load_lds_dwordx4 v[150:151], off
	s_waitcnt lgkmcnt(8)
	s_barrier
	s_waitcnt lgkmcnt(0)
	v_mfma_f32_16x16x32_bf16 v[124:127], v[142:145], v[162:165], v[124:127]
	v_mfma_f32_16x16x32_bf16 v[120:123], v[154:157], v[162:165], v[120:123]
	v_mfma_f32_16x16x32_bf16 v[116:119], v[142:145], v[170:173], v[116:119]
	v_mfma_f32_16x16x32_bf16 v[108:111], v[154:157], v[170:173], v[108:111]
	v_mfma_f32_16x16x32_bf16 v[100:103], v[142:145], v[180:183], v[100:103]
	v_mfma_f32_16x16x32_bf16 v[92:95], v[154:157], v[180:183], v[92:95]
	v_mfma_f32_16x16x32_bf16 v[84:87], v[142:145], v[188:191], v[84:87]
	v_mfma_f32_16x16x32_bf16 v[76:79], v[154:157], v[188:191], v[76:79]
	v_mfma_f32_16x16x32_bf16 v[124:127], v[146:149], v[166:169], v[124:127]
	v_mfma_f32_16x16x32_bf16 v[120:123], v[158:161], v[166:169], v[120:123]
	v_mfma_f32_16x16x32_bf16 v[116:119], v[146:149], v[174:177], v[116:119]
	v_mfma_f32_16x16x32_bf16 v[108:111], v[158:161], v[174:177], v[108:111]
	v_mfma_f32_16x16x32_bf16 v[100:103], v[146:149], v[184:187], v[100:103]
	v_mfma_f32_16x16x32_bf16 v[92:95], v[158:161], v[184:187], v[92:95]
	v_mfma_f32_16x16x32_bf16 v[84:87], v[146:149], v[192:195], v[84:87]
	v_mfma_f32_16x16x32_bf16 v[76:79], v[158:161], v[192:195], v[76:79]
	s_barrier
	s_add_i32 s28, 0, 0x14000
	v_add_u32_e32 v150, s28, v140
	s_add_i32 s21, s21, s16
	ds_read_b128 v[196:199], v150
	ds_read_b128 v[224:227], v150 offset:1024
	ds_read_b128 v[228:231], v150 offset:2048
	ds_read_b128 v[232:235], v150 offset:3072
	s_mov_b32 m0, s21
	s_nop 0
	global_load_lds_dwordx4 v178, s[12:13]
	s_add_i32 m0, s21, 0x2000
	s_nop 0
	global_load_lds_dwordx4 v128, s[12:13]
	s_barrier
	s_waitcnt lgkmcnt(0)
	v_mfma_f32_16x16x32_bf16 v[112:115], v[196:199], v[162:165], v[112:115]
	v_mfma_f32_16x16x32_bf16 v[104:107], v[228:231], v[162:165], v[104:107]
	v_mfma_f32_16x16x32_bf16 v[96:99], v[196:199], v[170:173], v[96:99]
	v_mfma_f32_16x16x32_bf16 v[88:91], v[228:231], v[170:173], v[88:91]
	v_mfma_f32_16x16x32_bf16 v[80:83], v[196:199], v[180:183], v[80:83]
	v_mfma_f32_16x16x32_bf16 v[72:75], v[228:231], v[180:183], v[72:75]
	v_mfma_f32_16x16x32_bf16 v[68:71], v[196:199], v[188:191], v[68:71]
	v_mfma_f32_16x16x32_bf16 v[64:67], v[228:231], v[188:191], v[64:67]
	v_mfma_f32_16x16x32_bf16 v[112:115], v[224:227], v[166:169], v[112:115]
	v_mfma_f32_16x16x32_bf16 v[104:107], v[232:235], v[166:169], v[104:107]
	v_mfma_f32_16x16x32_bf16 v[96:99], v[224:227], v[174:177], v[96:99]
	v_mfma_f32_16x16x32_bf16 v[88:91], v[232:235], v[174:177], v[88:91]
	v_mfma_f32_16x16x32_bf16 v[80:83], v[224:227], v[184:187], v[80:83]
	v_mfma_f32_16x16x32_bf16 v[72:75], v[232:235], v[184:187], v[72:75]
	v_mfma_f32_16x16x32_bf16 v[68:71], v[224:227], v[192:195], v[68:71]
	v_mfma_f32_16x16x32_bf16 v[64:67], v[232:235], v[192:195], v[64:67]
	s_mov_b32 m0, s22
	s_mov_b64 s[100:101], s[14:15]
	s_barrier
	ds_read_b128 v[162:165], v141 offset:16384
	ds_read_b128 v[166:169], v141 offset:17408
	ds_read_b128 v[170:173], v141 offset:18432
	ds_read_b128 v[174:177], v141 offset:19456
	ds_read_b128 v[180:183], v141 offset:20480
	ds_read_b128 v[184:187], v141 offset:21504
	ds_read_b128 v[188:191], v141 offset:22528
	ds_read_b128 v[192:195], v141 offset:23552
	global_load_lds_dwordx4 v132, s[14:15]
	s_mov_b32 m0, s23
	s_mov_b64 s[100:101], s[14:15]
	global_load_lds_dwordx4 v130, s[14:15]
	s_barrier
	s_waitcnt lgkmcnt(0)
	v_mfma_f32_16x16x32_bf16 v[60:63], v[142:145], v[162:165], v[60:63]
	v_mfma_f32_16x16x32_bf16 v[56:59], v[154:157], v[162:165], v[56:59]
	v_mfma_f32_16x16x32_bf16 v[52:55], v[142:145], v[170:173], v[52:55]
	v_mfma_f32_16x16x32_bf16 v[44:47], v[154:157], v[170:173], v[44:47]
	v_mfma_f32_16x16x32_bf16 v[36:39], v[142:145], v[180:183], v[36:39]
	v_mfma_f32_16x16x32_bf16 v[28:31], v[154:157], v[180:183], v[28:31]
	v_mfma_f32_16x16x32_bf16 v[20:23], v[142:145], v[188:191], v[20:23]
	v_mfma_f32_16x16x32_bf16 v[12:15], v[154:157], v[188:191], v[12:15]
	v_mfma_f32_16x16x32_bf16 v[60:63], v[146:149], v[166:169], v[60:63]
	v_mfma_f32_16x16x32_bf16 v[56:59], v[158:161], v[166:169], v[56:59]
	v_mfma_f32_16x16x32_bf16 v[52:55], v[146:149], v[174:177], v[52:55]
	v_mfma_f32_16x16x32_bf16 v[44:47], v[158:161], v[174:177], v[44:47]
	v_mfma_f32_16x16x32_bf16 v[36:39], v[146:149], v[184:187], v[36:39]
	v_mfma_f32_16x16x32_bf16 v[28:31], v[158:161], v[184:187], v[28:31]
	v_mfma_f32_16x16x32_bf16 v[20:23], v[146:149], v[192:195], v[20:23]
	v_mfma_f32_16x16x32_bf16 v[12:15], v[158:161], v[192:195], v[12:15]
	s_barrier
	s_add_u32 s26, s12, 0x20000
	s_addc_u32 s27, s13, 0
	s_add_i32 s21, s28, s16
	s_mov_b32 m0, s21
	s_nop 0
	global_load_lds_dwordx4 v178, s[26:27]
	s_add_i32 m0, s21, 0x2000
	s_nop 0
	global_load_lds_dwordx4 v128, s[26:27]
	s_waitcnt vmcnt(6)
	s_barrier
	v_mfma_f32_16x16x32_bf16 v[48:51], v[196:199], v[162:165], v[48:51]
	v_mfma_f32_16x16x32_bf16 v[40:43], v[228:231], v[162:165], v[40:43]
	v_mfma_f32_16x16x32_bf16 v[32:35], v[196:199], v[170:173], v[32:35]
	v_mfma_f32_16x16x32_bf16 v[24:27], v[228:231], v[170:173], v[24:27]
	v_mfma_f32_16x16x32_bf16 v[16:19], v[196:199], v[180:183], v[16:19]
	v_mfma_f32_16x16x32_bf16 v[8:11], v[228:231], v[180:183], v[8:11]
	v_mfma_f32_16x16x32_bf16 v[4:7], v[196:199], v[188:191], v[4:7]
	v_mfma_f32_16x16x32_bf16 v[0:3], v[228:231], v[188:191], v[0:3]
	v_mfma_f32_16x16x32_bf16 v[48:51], v[224:227], v[166:169], v[48:51]
	v_mfma_f32_16x16x32_bf16 v[40:43], v[232:235], v[166:169], v[40:43]
	v_mfma_f32_16x16x32_bf16 v[32:35], v[224:227], v[174:177], v[32:35]
	v_mfma_f32_16x16x32_bf16 v[24:27], v[232:235], v[174:177], v[24:27]
	v_mfma_f32_16x16x32_bf16 v[16:19], v[224:227], v[184:187], v[16:19]
	v_mfma_f32_16x16x32_bf16 v[8:11], v[232:235], v[184:187], v[8:11]
	v_mfma_f32_16x16x32_bf16 v[4:7], v[224:227], v[192:195], v[4:7]
	v_mfma_f32_16x16x32_bf16 v[0:3], v[232:235], v[192:195], v[0:3]
	s_add_i32 s21, 0, 0x18000
	v_add_u32_e32 v153, s21, v140
	s_barrier
	ds_read_b128 v[142:145], v153
	ds_read_b128 v[146:149], v153 offset:1024
	ds_read_b128 v[154:157], v153 offset:2048
	ds_read_b128 v[158:161], v153 offset:3072
	s_add_u32 s14, s14, 0x20000
	s_addc_u32 s15, s15, 0
	s_mov_b32 m0, s24
	ds_read_b128 v[162:165], v141 offset:32768
	ds_read_b128 v[166:169], v141 offset:33792
	ds_read_b128 v[170:173], v141 offset:34816
	ds_read_b128 v[174:177], v141 offset:35840
	ds_read_b128 v[180:183], v141 offset:36864
	ds_read_b128 v[184:187], v141 offset:37888
	ds_read_b128 v[188:191], v141 offset:38912
	ds_read_b128 v[192:195], v141 offset:39936
	global_load_lds_dwordx4 v132, s[14:15]
	s_mov_b32 m0, s25
	s_nop 0
	global_load_lds_dwordx4 v130, s[14:15]
	s_waitcnt lgkmcnt(8)
	s_barrier
	s_waitcnt lgkmcnt(0)
	v_mfma_f32_16x16x32_bf16 v[124:127], v[142:145], v[162:165], v[124:127]
	v_mfma_f32_16x16x32_bf16 v[120:123], v[154:157], v[162:165], v[120:123]
	v_mfma_f32_16x16x32_bf16 v[116:119], v[142:145], v[170:173], v[116:119]
	v_mfma_f32_16x16x32_bf16 v[108:111], v[154:157], v[170:173], v[108:111]
	v_mfma_f32_16x16x32_bf16 v[100:103], v[142:145], v[180:183], v[100:103]
	v_mfma_f32_16x16x32_bf16 v[92:95], v[154:157], v[180:183], v[92:95]
	v_mfma_f32_16x16x32_bf16 v[84:87], v[142:145], v[188:191], v[84:87]
	v_mfma_f32_16x16x32_bf16 v[76:79], v[154:157], v[188:191], v[76:79]
	v_mfma_f32_16x16x32_bf16 v[124:127], v[146:149], v[166:169], v[124:127]
	v_mfma_f32_16x16x32_bf16 v[120:123], v[158:161], v[166:169], v[120:123]
	v_mfma_f32_16x16x32_bf16 v[116:119], v[146:149], v[174:177], v[116:119]
	v_mfma_f32_16x16x32_bf16 v[108:111], v[158:161], v[174:177], v[108:111]
	v_mfma_f32_16x16x32_bf16 v[100:103], v[146:149], v[184:187], v[100:103]
	v_mfma_f32_16x16x32_bf16 v[92:95], v[158:161], v[184:187], v[92:95]
	v_mfma_f32_16x16x32_bf16 v[84:87], v[146:149], v[192:195], v[84:87]
	v_mfma_f32_16x16x32_bf16 v[76:79], v[158:161], v[192:195], v[76:79]
	s_barrier
	s_add_i32 s14, 0, 0x1c000
	s_add_i32 s15, s21, s16
	v_add_u32_e32 v153, s14, v140
	s_add_i32 m0, s15, 0xffffff80
	ds_read_b128 v[196:199], v153
	ds_read_b128 v[224:227], v153 offset:1024
	ds_read_b128 v[228:231], v153 offset:2048
	ds_read_b128 v[232:235], v153 offset:3072
	global_load_lds_dwordx4 v178, s[12:13] offset:128
	s_add_i32 m0, s15, 0x1f80
	s_nop 0
	global_load_lds_dwordx4 v128, s[12:13] offset:128
	s_barrier
	s_waitcnt lgkmcnt(0)
	v_mfma_f32_16x16x32_bf16 v[112:115], v[196:199], v[162:165], v[112:115]
	v_mfma_f32_16x16x32_bf16 v[104:107], v[228:231], v[162:165], v[104:107]
	v_mfma_f32_16x16x32_bf16 v[96:99], v[196:199], v[170:173], v[96:99]
	v_mfma_f32_16x16x32_bf16 v[88:91], v[228:231], v[170:173], v[88:91]
	v_mfma_f32_16x16x32_bf16 v[80:83], v[196:199], v[180:183], v[80:83]
	v_mfma_f32_16x16x32_bf16 v[72:75], v[228:231], v[180:183], v[72:75]
	v_mfma_f32_16x16x32_bf16 v[68:71], v[196:199], v[188:191], v[68:71]
	v_mfma_f32_16x16x32_bf16 v[64:67], v[228:231], v[188:191], v[64:67]
	v_mfma_f32_16x16x32_bf16 v[112:115], v[224:227], v[166:169], v[112:115]
	v_mfma_f32_16x16x32_bf16 v[104:107], v[232:235], v[166:169], v[104:107]
	v_mfma_f32_16x16x32_bf16 v[96:99], v[224:227], v[174:177], v[96:99]
	v_mfma_f32_16x16x32_bf16 v[88:91], v[232:235], v[174:177], v[88:91]
	v_mfma_f32_16x16x32_bf16 v[80:83], v[224:227], v[184:187], v[80:83]
	v_mfma_f32_16x16x32_bf16 v[72:75], v[232:235], v[184:187], v[72:75]
	v_mfma_f32_16x16x32_bf16 v[68:71], v[224:227], v[192:195], v[68:71]
	v_mfma_f32_16x16x32_bf16 v[64:67], v[232:235], v[192:195], v[64:67]
	s_add_i32 m0, s18, 0xffffff80
	s_barrier
	ds_read_b128 v[162:165], v141 offset:49152
	ds_read_b128 v[166:169], v141 offset:50176
	ds_read_b128 v[170:173], v141 offset:51200
	ds_read_b128 v[174:177], v141 offset:52224
	ds_read_b128 v[180:183], v141 offset:53248
	ds_read_b128 v[184:187], v141 offset:54272
	ds_read_b128 v[188:191], v141 offset:55296
	ds_read_b128 v[192:195], v141 offset:56320
	global_load_lds_dwordx4 v132, s[100:101] offset:128
	s_add_i32 m0, s19, 0xffffff80
	s_nop 0
	global_load_lds_dwordx4 v130, s[100:101] offset:128
	s_barrier
	s_waitcnt lgkmcnt(0)
	v_mfma_f32_16x16x32_bf16 v[60:63], v[142:145], v[162:165], v[60:63]
	v_mfma_f32_16x16x32_bf16 v[56:59], v[154:157], v[162:165], v[56:59]
	v_mfma_f32_16x16x32_bf16 v[52:55], v[142:145], v[170:173], v[52:55]
	v_mfma_f32_16x16x32_bf16 v[44:47], v[154:157], v[170:173], v[44:47]
	v_mfma_f32_16x16x32_bf16 v[36:39], v[142:145], v[180:183], v[36:39]
	v_mfma_f32_16x16x32_bf16 v[28:31], v[154:157], v[180:183], v[28:31]
	v_mfma_f32_16x16x32_bf16 v[20:23], v[142:145], v[188:191], v[20:23]
	v_mfma_f32_16x16x32_bf16 v[12:15], v[154:157], v[188:191], v[12:15]
	v_mfma_f32_16x16x32_bf16 v[60:63], v[146:149], v[166:169], v[60:63]
	v_mfma_f32_16x16x32_bf16 v[56:59], v[158:161], v[166:169], v[56:59]
	v_mfma_f32_16x16x32_bf16 v[52:55], v[146:149], v[174:177], v[52:55]
	v_mfma_f32_16x16x32_bf16 v[44:47], v[158:161], v[174:177], v[44:47]
	v_mfma_f32_16x16x32_bf16 v[36:39], v[146:149], v[184:187], v[36:39]
	v_mfma_f32_16x16x32_bf16 v[28:31], v[158:161], v[184:187], v[28:31]
	v_mfma_f32_16x16x32_bf16 v[20:23], v[146:149], v[192:195], v[20:23]
	v_mfma_f32_16x16x32_bf16 v[12:15], v[158:161], v[192:195], v[12:15]
	s_barrier
	s_add_u32 s12, s12, 0x20080
	s_addc_u32 s13, s13, 0
	s_add_i32 s14, s14, s16
	s_mov_b32 m0, s14
	s_nop 0
	global_load_lds_dwordx4 v178, s[12:13]
	s_add_i32 m0, s14, 0x2000
	s_nop 0
	global_load_lds_dwordx4 v128, s[12:13]
	s_waitcnt vmcnt(6)
	s_barrier
	v_mfma_f32_16x16x32_bf16 v[48:51], v[196:199], v[162:165], v[48:51]
	v_mfma_f32_16x16x32_bf16 v[40:43], v[228:231], v[162:165], v[40:43]
	v_mfma_f32_16x16x32_bf16 v[32:35], v[196:199], v[170:173], v[32:35]
	v_mfma_f32_16x16x32_bf16 v[24:27], v[228:231], v[170:173], v[24:27]
	v_mfma_f32_16x16x32_bf16 v[16:19], v[196:199], v[180:183], v[16:19]
	v_mfma_f32_16x16x32_bf16 v[8:11], v[228:231], v[180:183], v[8:11]
	v_mfma_f32_16x16x32_bf16 v[4:7], v[196:199], v[188:191], v[4:7]
	v_mfma_f32_16x16x32_bf16 v[0:3], v[228:231], v[188:191], v[0:3]
	v_mfma_f32_16x16x32_bf16 v[48:51], v[224:227], v[166:169], v[48:51]
	v_mfma_f32_16x16x32_bf16 v[40:43], v[232:235], v[166:169], v[40:43]
	v_mfma_f32_16x16x32_bf16 v[32:35], v[224:227], v[174:177], v[32:35]
	v_mfma_f32_16x16x32_bf16 v[24:27], v[232:235], v[174:177], v[24:27]
	v_mfma_f32_16x16x32_bf16 v[16:19], v[224:227], v[184:187], v[16:19]
	v_mfma_f32_16x16x32_bf16 v[8:11], v[232:235], v[184:187], v[8:11]
	v_mfma_f32_16x16x32_bf16 v[4:7], v[224:227], v[192:195], v[4:7]
	v_mfma_f32_16x16x32_bf16 v[0:3], v[232:235], v[192:195], v[0:3]
	s_add_i32 s20, s20, 2
	s_add_u32 s10, s10, 0x100
	s_addc_u32 s11, s11, 0
	s_cmp_gt_u32 s20, 5
	s_barrier
	s_cbranch_scc0 .LBB0_943
	v_readlane_b32 s6, v254, 23
	s_or_b32 s6, s17, s6
	v_cvt_pk_bf16_f32 v124, v124, v125
	v_cvt_pk_bf16_f32 v125, v126, v127
	v_cvt_pk_bf16_f32 v126, v120, v121
	v_cvt_pk_bf16_f32 v127, v122, v123
	s_nop 0
	v_or_b32_e32 v132, s6, v139
	v_readlane_b32 s6, v254, 25
	v_lshlrev_b32_e32 v178, 1, v132
	s_nop 0
	v_add_u32_e32 v128, s6, v138
	v_ashrrev_i32_e32 v129, 31, v128
	v_lshlrev_b64 v[130:131], 12, v[128:129]
	v_lshl_add_u64 v[130:131], s[4:5], 0, v[130:131]
	v_lshl_add_u64 v[130:131], v[130:131], 0, v[178:179]
	global_store_dwordx4 v[130:131], v[124:127], off
	v_cvt_pk_bf16_f32 v112, v112, v113
	v_cvt_pk_bf16_f32 v113, v114, v115
	v_cvt_pk_bf16_f32 v114, v104, v105
	v_or_b32_e32 v104, 16, v128
	v_ashrrev_i32_e32 v105, 31, v104
	v_lshlrev_b64 v[104:105], 12, v[104:105]
	v_lshl_add_u64 v[104:105], s[4:5], 0, v[104:105]
	v_cvt_pk_bf16_f32 v115, v106, v107
	global_store_dwordx4 v[130:131], v[112:115], off offset:256
	s_nop 1
	v_lshl_add_u64 v[112:113], v[104:105], 0, v[178:179]
	v_cvt_pk_bf16_f32 v104, v116, v117
	v_cvt_pk_bf16_f32 v105, v118, v119
	v_cvt_pk_bf16_f32 v106, v108, v109
	v_cvt_pk_bf16_f32 v107, v110, v111
	global_store_dwordx4 v[112:113], v[104:107], off
	v_cvt_pk_bf16_f32 v96, v96, v97
	v_cvt_pk_bf16_f32 v97, v98, v99
	v_cvt_pk_bf16_f32 v98, v88, v89
	v_or_b32_e32 v88, 32, v128
	v_ashrrev_i32_e32 v89, 31, v88
	v_lshlrev_b64 v[88:89], 12, v[88:89]
	v_lshl_add_u64 v[88:89], s[4:5], 0, v[88:89]
	v_cvt_pk_bf16_f32 v99, v90, v91
	global_store_dwordx4 v[112:113], v[96:99], off offset:256
	s_nop 1
	v_lshl_add_u64 v[96:97], v[88:89], 0, v[178:179]
	v_cvt_pk_bf16_f32 v88, v100, v101
	v_cvt_pk_bf16_f32 v89, v102, v103
	v_cvt_pk_bf16_f32 v90, v92, v93
	v_cvt_pk_bf16_f32 v91, v94, v95
	global_store_dwordx4 v[96:97], v[88:91], off
	v_cvt_pk_bf16_f32 v80, v80, v81
	v_cvt_pk_bf16_f32 v81, v82, v83
	v_cvt_pk_bf16_f32 v82, v72, v73
	v_or_b32_e32 v72, 48, v128
	v_ashrrev_i32_e32 v73, 31, v72
	v_lshlrev_b64 v[72:73], 12, v[72:73]
	v_lshl_add_u64 v[72:73], s[4:5], 0, v[72:73]
	v_cvt_pk_bf16_f32 v83, v74, v75
	global_store_dwordx4 v[96:97], v[80:83], off offset:256
	s_nop 1
	v_lshl_add_u64 v[80:81], v[72:73], 0, v[178:179]
	v_cvt_pk_bf16_f32 v72, v84, v85
	v_cvt_pk_bf16_f32 v73, v86, v87
	v_cvt_pk_bf16_f32 v74, v76, v77
	v_cvt_pk_bf16_f32 v75, v78, v79
	global_store_dwordx4 v[80:81], v[72:75], off
	v_cvt_pk_bf16_f32 v68, v68, v69
	v_cvt_pk_bf16_f32 v69, v70, v71
	v_cvt_pk_bf16_f32 v70, v64, v65
	v_add_u32_e32 v64, 0x80, v128
	v_ashrrev_i32_e32 v65, 31, v64
	v_lshlrev_b64 v[64:65], 12, v[64:65]
	v_lshl_add_u64 v[64:65], s[4:5], 0, v[64:65]
	v_lshl_add_u64 v[64:65], v[64:65], 0, v[178:179]
	v_cvt_pk_bf16_f32 v71, v66, v67
	global_store_dwordx4 v[80:81], v[68:71], off offset:256
	v_cvt_pk_bf16_f32 v60, v60, v61
	v_cvt_pk_bf16_f32 v61, v62, v63
	v_cvt_pk_bf16_f32 v62, v56, v57
	v_cvt_pk_bf16_f32 v63, v58, v59
	global_store_dwordx4 v[64:65], v[60:63], off
	v_cvt_pk_bf16_f32 v48, v48, v49
	v_cvt_pk_bf16_f32 v49, v50, v51
	v_cvt_pk_bf16_f32 v50, v40, v41
	v_add_u32_e32 v40, 0x90, v128
	v_ashrrev_i32_e32 v41, 31, v40
	v_lshlrev_b64 v[40:41], 12, v[40:41]
	v_lshl_add_u64 v[40:41], s[4:5], 0, v[40:41]
	v_cvt_pk_bf16_f32 v51, v42, v43
	global_store_dwordx4 v[64:65], v[48:51], off offset:256
	s_nop 1
	v_lshl_add_u64 v[48:49], v[40:41], 0, v[178:179]
	v_cvt_pk_bf16_f32 v40, v52, v53
	v_cvt_pk_bf16_f32 v41, v54, v55
	v_cvt_pk_bf16_f32 v42, v44, v45
	v_cvt_pk_bf16_f32 v43, v46, v47
	global_store_dwordx4 v[48:49], v[40:43], off
	v_cvt_pk_bf16_f32 v32, v32, v33
	v_cvt_pk_bf16_f32 v33, v34, v35
	v_cvt_pk_bf16_f32 v34, v24, v25
	v_add_u32_e32 v24, 0xa0, v128
	v_ashrrev_i32_e32 v25, 31, v24
	v_lshlrev_b64 v[24:25], 12, v[24:25]
	v_lshl_add_u64 v[24:25], s[4:5], 0, v[24:25]
	v_cvt_pk_bf16_f32 v35, v26, v27
	global_store_dwordx4 v[48:49], v[32:35], off offset:256
	s_nop 1
	v_lshl_add_u64 v[32:33], v[24:25], 0, v[178:179]
	v_cvt_pk_bf16_f32 v24, v36, v37
	v_cvt_pk_bf16_f32 v25, v38, v39
	v_cvt_pk_bf16_f32 v26, v28, v29
	v_cvt_pk_bf16_f32 v27, v30, v31
	global_store_dwordx4 v[32:33], v[24:27], off
	v_cvt_pk_bf16_f32 v16, v16, v17
	v_cvt_pk_bf16_f32 v17, v18, v19
	v_cvt_pk_bf16_f32 v18, v8, v9
	v_add_u32_e32 v8, 0xb0, v128
	v_ashrrev_i32_e32 v9, 31, v8
	v_lshlrev_b64 v[8:9], 12, v[8:9]
	v_lshl_add_u64 v[8:9], s[4:5], 0, v[8:9]
	v_cvt_pk_bf16_f32 v19, v10, v11
	global_store_dwordx4 v[32:33], v[16:19], off offset:256
	v_readlane_b32 s4, v255, 8
	s_nop 0
	v_lshl_add_u64 v[16:17], v[8:9], 0, v[178:179]
	v_cvt_pk_bf16_f32 v8, v20, v21
	v_cvt_pk_bf16_f32 v9, v22, v23
	v_cvt_pk_bf16_f32 v10, v12, v13
	v_cvt_pk_bf16_f32 v11, v14, v15
	global_store_dwordx4 v[16:17], v[8:11], off
	v_cvt_pk_bf16_f32 v4, v4, v5
	v_cvt_pk_bf16_f32 v5, v6, v7
	v_cvt_pk_bf16_f32 v6, v0, v1
	v_cvt_pk_bf16_f32 v7, v2, v3
	global_store_dwordx4 v[16:17], v[4:7], off offset:256
	s_waitcnt vmcnt(0)
	s_cmp_lt_u32 s4, 4
	s_cbranch_scc0 .LBB0_946
	s_barrier

.LBB0_1077:
	s_add_u32 s18, s16, 0x100
	s_addc_u32 s19, s17, 0
	s_add_i32 s66, 0, 0x10000
	v_add_u32_e32 v140, s66, v157
	ds_read_b128 v[128:131], v140
	ds_read_b128 v[132:135], v140 offset:1024
	ds_read_b128 v[136:139], v140 offset:2048
	ds_read_b128 v[140:143], v140 offset:3072
	s_cmp_eq_u32 s63, 28
	s_cselect_b32 s23, s13, s19
	s_cselect_b32 s22, s12, s18
	s_cselect_b32 s21, s15, s62
	s_cselect_b32 s20, s14, s5
	v_lshl_add_u64 v[154:155], s[16:17], 0, v[148:149]
	s_add_i32 m0, s29, 0xc000
	ds_read_b128 v[150:153], v159
	ds_read_b128 v[160:163], v159 offset:1024
	ds_read_b128 v[164:167], v159 offset:2048
	ds_read_b128 v[168:171], v159 offset:3072
	ds_read_b128 v[172:175], v159 offset:4096
	ds_read_b128 v[180:183], v159 offset:5120
	ds_read_b128 v[184:187], v159 offset:6144
	ds_read_b128 v[188:191], v159 offset:7168
	global_load_lds_dwordx4 v[154:155], off
	v_lshl_add_u64 v[154:155], s[16:17], 0, v[146:147]
	s_add_i32 m0, s29, 0xe000
	s_nop 0
	global_load_lds_dwordx4 v[154:155], off
	s_waitcnt lgkmcnt(8)
	s_barrier
	s_waitcnt lgkmcnt(0)
	v_mfma_f32_16x16x32_bf16 v[124:127], v[128:131], v[150:153], v[124:127]
	v_mfma_f32_16x16x32_bf16 v[120:123], v[136:139], v[150:153], v[120:123]
	v_mfma_f32_16x16x32_bf16 v[108:111], v[128:131], v[164:167], v[108:111]
	v_mfma_f32_16x16x32_bf16 v[104:107], v[136:139], v[164:167], v[104:107]
	v_mfma_f32_16x16x32_bf16 v[92:95], v[128:131], v[172:175], v[92:95]
	v_mfma_f32_16x16x32_bf16 v[88:91], v[136:139], v[172:175], v[88:91]
	v_mfma_f32_16x16x32_bf16 v[76:79], v[128:131], v[184:187], v[76:79]
	v_mfma_f32_16x16x32_bf16 v[72:75], v[136:139], v[184:187], v[72:75]
	v_mfma_f32_16x16x32_bf16 v[124:127], v[132:135], v[160:163], v[124:127]
	v_mfma_f32_16x16x32_bf16 v[120:123], v[140:143], v[160:163], v[120:123]
	v_mfma_f32_16x16x32_bf16 v[108:111], v[132:135], v[168:171], v[108:111]
	v_mfma_f32_16x16x32_bf16 v[104:107], v[140:143], v[168:171], v[104:107]
	v_mfma_f32_16x16x32_bf16 v[92:95], v[132:135], v[180:183], v[92:95]
	v_mfma_f32_16x16x32_bf16 v[88:91], v[140:143], v[180:183], v[88:91]
	v_mfma_f32_16x16x32_bf16 v[76:79], v[132:135], v[188:191], v[76:79]
	v_mfma_f32_16x16x32_bf16 v[72:75], v[140:143], v[188:191], v[72:75]
	s_barrier
	s_add_i32 s67, 0, 0x14000
	v_add_u32_e32 v154, s67, v157
	s_add_i32 s16, s66, s28
	ds_read_b128 v[192:195], v154
	ds_read_b128 v[196:199], v154 offset:1024
	ds_read_b128 v[204:207], v154 offset:2048
	ds_read_b128 v[212:215], v154 offset:3072
	s_mov_b32 m0, s16
	s_nop 0
	global_load_lds_dwordx4 v178, s[20:21]
	s_add_i32 m0, s16, 0x2000
	s_nop 0
	global_load_lds_dwordx4 v144, s[20:21]
	s_barrier
	s_waitcnt lgkmcnt(0)
	v_mfma_f32_16x16x32_bf16 v[116:119], v[192:195], v[150:153], v[116:119]
	v_mfma_f32_16x16x32_bf16 v[112:115], v[204:207], v[150:153], v[112:115]
	v_mfma_f32_16x16x32_bf16 v[100:103], v[192:195], v[164:167], v[100:103]
	v_mfma_f32_16x16x32_bf16 v[96:99], v[204:207], v[164:167], v[96:99]
	v_mfma_f32_16x16x32_bf16 v[84:87], v[192:195], v[172:175], v[84:87]
	v_mfma_f32_16x16x32_bf16 v[80:83], v[204:207], v[172:175], v[80:83]
	v_mfma_f32_16x16x32_bf16 v[68:71], v[192:195], v[184:187], v[68:71]
	v_mfma_f32_16x16x32_bf16 v[64:67], v[204:207], v[184:187], v[64:67]
	v_mfma_f32_16x16x32_bf16 v[116:119], v[196:199], v[160:163], v[116:119]
	v_mfma_f32_16x16x32_bf16 v[112:115], v[212:215], v[160:163], v[112:115]
	v_mfma_f32_16x16x32_bf16 v[100:103], v[196:199], v[168:171], v[100:103]
	v_mfma_f32_16x16x32_bf16 v[96:99], v[212:215], v[168:171], v[96:99]
	v_mfma_f32_16x16x32_bf16 v[84:87], v[196:199], v[180:183], v[84:87]
	v_mfma_f32_16x16x32_bf16 v[80:83], v[212:215], v[180:183], v[80:83]
	v_mfma_f32_16x16x32_bf16 v[68:71], v[196:199], v[188:191], v[68:71]
	v_mfma_f32_16x16x32_bf16 v[64:67], v[212:215], v[188:191], v[64:67]
	s_mov_b32 m0, s29
	s_mov_b64 s[100:101], s[22:23]
	s_barrier
	ds_read_b128 v[150:153], v159 offset:16384
	ds_read_b128 v[160:163], v159 offset:17408
	ds_read_b128 v[164:167], v159 offset:18432
	ds_read_b128 v[168:171], v159 offset:19456
	ds_read_b128 v[172:175], v159 offset:20480
	ds_read_b128 v[180:183], v159 offset:21504
	ds_read_b128 v[184:187], v159 offset:22528
	ds_read_b128 v[188:191], v159 offset:23552
	global_load_lds_dwordx4 v178, s[22:23]
	s_mov_b32 m0, s30
	s_mov_b64 s[100:101], s[22:23]
	global_load_lds_dwordx4 v144, s[22:23]
	s_barrier
	s_waitcnt lgkmcnt(0)
	v_mfma_f32_16x16x32_bf16 v[60:63], v[128:131], v[150:153], v[60:63]
	v_mfma_f32_16x16x32_bf16 v[56:59], v[136:139], v[150:153], v[56:59]
	v_mfma_f32_16x16x32_bf16 v[44:47], v[128:131], v[164:167], v[44:47]
	v_mfma_f32_16x16x32_bf16 v[40:43], v[136:139], v[164:167], v[40:43]
	v_mfma_f32_16x16x32_bf16 v[28:31], v[128:131], v[172:175], v[28:31]
	v_mfma_f32_16x16x32_bf16 v[24:27], v[136:139], v[172:175], v[24:27]
	v_mfma_f32_16x16x32_bf16 v[12:15], v[128:131], v[184:187], v[12:15]
	v_mfma_f32_16x16x32_bf16 v[8:11], v[136:139], v[184:187], v[8:11]
	v_mfma_f32_16x16x32_bf16 v[60:63], v[132:135], v[160:163], v[60:63]
	v_mfma_f32_16x16x32_bf16 v[56:59], v[140:143], v[160:163], v[56:59]
	v_mfma_f32_16x16x32_bf16 v[44:47], v[132:135], v[168:171], v[44:47]
	v_mfma_f32_16x16x32_bf16 v[40:43], v[140:143], v[168:171], v[40:43]
	v_mfma_f32_16x16x32_bf16 v[28:31], v[132:135], v[180:183], v[28:31]
	v_mfma_f32_16x16x32_bf16 v[24:27], v[140:143], v[180:183], v[24:27]
	v_mfma_f32_16x16x32_bf16 v[12:15], v[132:135], v[188:191], v[12:15]
	v_mfma_f32_16x16x32_bf16 v[8:11], v[140:143], v[188:191], v[8:11]
	s_barrier
	s_add_u32 s16, s20, 0x80000
	s_addc_u32 s17, s21, 0
	s_add_i32 s66, s67, s28
	s_mov_b32 m0, s66
	s_nop 0
	global_load_lds_dwordx4 v178, s[16:17]
	s_add_i32 m0, s66, 0x2000
	s_nop 0
	global_load_lds_dwordx4 v144, s[16:17]
	s_waitcnt vmcnt(6)
	s_barrier
	v_mfma_f32_16x16x32_bf16 v[52:55], v[192:195], v[150:153], v[52:55]
	v_mfma_f32_16x16x32_bf16 v[48:51], v[204:207], v[150:153], v[48:51]
	v_mfma_f32_16x16x32_bf16 v[36:39], v[192:195], v[164:167], v[36:39]
	v_mfma_f32_16x16x32_bf16 v[32:35], v[204:207], v[164:167], v[32:35]
	v_mfma_f32_16x16x32_bf16 v[20:23], v[192:195], v[172:175], v[20:23]
	v_mfma_f32_16x16x32_bf16 v[16:19], v[204:207], v[172:175], v[16:19]
	v_mfma_f32_16x16x32_bf16 v[4:7], v[192:195], v[184:187], v[4:7]
	v_mfma_f32_16x16x32_bf16 v[0:3], v[204:207], v[184:187], v[0:3]
	v_mfma_f32_16x16x32_bf16 v[52:55], v[196:199], v[160:163], v[52:55]
	v_mfma_f32_16x16x32_bf16 v[48:51], v[212:215], v[160:163], v[48:51]
	v_mfma_f32_16x16x32_bf16 v[36:39], v[196:199], v[168:171], v[36:39]
	v_mfma_f32_16x16x32_bf16 v[32:35], v[212:215], v[168:171], v[32:35]
	v_mfma_f32_16x16x32_bf16 v[20:23], v[196:199], v[180:183], v[20:23]
	v_mfma_f32_16x16x32_bf16 v[16:19], v[212:215], v[180:183], v[16:19]
	v_mfma_f32_16x16x32_bf16 v[4:7], v[196:199], v[188:191], v[4:7]
	v_mfma_f32_16x16x32_bf16 v[0:3], v[212:215], v[188:191], v[0:3]
	s_add_i32 s66, 0, 0x18000
	v_add_u32_e32 v140, s66, v157
	s_barrier
	ds_read_b128 v[128:131], v140
	ds_read_b128 v[132:135], v140 offset:1024
	ds_read_b128 v[136:139], v140 offset:2048
	ds_read_b128 v[140:143], v140 offset:3072
	s_add_u32 s16, s22, 0x80000
	s_addc_u32 s17, s23, 0
	s_mov_b32 m0, s31
	ds_read_b128 v[150:153], v159 offset:32768
	ds_read_b128 v[160:163], v159 offset:33792
	ds_read_b128 v[164:167], v159 offset:34816
	ds_read_b128 v[168:171], v159 offset:35840
	ds_read_b128 v[172:175], v159 offset:36864
	ds_read_b128 v[180:183], v159 offset:37888
	ds_read_b128 v[184:187], v159 offset:38912
	ds_read_b128 v[188:191], v159 offset:39936
	global_load_lds_dwordx4 v178, s[16:17]
	s_mov_b32 m0, s34
	s_nop 0
	global_load_lds_dwordx4 v144, s[16:17]
	s_waitcnt lgkmcnt(8)
	s_barrier
	s_waitcnt lgkmcnt(0)
	v_mfma_f32_16x16x32_bf16 v[124:127], v[128:131], v[150:153], v[124:127]
	v_mfma_f32_16x16x32_bf16 v[120:123], v[136:139], v[150:153], v[120:123]
	v_mfma_f32_16x16x32_bf16 v[108:111], v[128:131], v[164:167], v[108:111]
	v_mfma_f32_16x16x32_bf16 v[104:107], v[136:139], v[164:167], v[104:107]
	v_mfma_f32_16x16x32_bf16 v[92:95], v[128:131], v[172:175], v[92:95]
	v_mfma_f32_16x16x32_bf16 v[88:91], v[136:139], v[172:175], v[88:91]
	v_mfma_f32_16x16x32_bf16 v[76:79], v[128:131], v[184:187], v[76:79]
	v_mfma_f32_16x16x32_bf16 v[72:75], v[136:139], v[184:187], v[72:75]
	v_mfma_f32_16x16x32_bf16 v[124:127], v[132:135], v[160:163], v[124:127]
	v_mfma_f32_16x16x32_bf16 v[120:123], v[140:143], v[160:163], v[120:123]
	v_mfma_f32_16x16x32_bf16 v[108:111], v[132:135], v[168:171], v[108:111]
	v_mfma_f32_16x16x32_bf16 v[104:107], v[140:143], v[168:171], v[104:107]
	v_mfma_f32_16x16x32_bf16 v[92:95], v[132:135], v[180:183], v[92:95]
	v_mfma_f32_16x16x32_bf16 v[88:91], v[140:143], v[180:183], v[88:91]
	v_mfma_f32_16x16x32_bf16 v[76:79], v[132:135], v[188:191], v[76:79]
	v_mfma_f32_16x16x32_bf16 v[72:75], v[140:143], v[188:191], v[72:75]
	s_barrier
	s_add_i32 s22, 0, 0x1c000
	s_add_i32 s16, s66, s28
	v_add_u32_e32 v212, s22, v157
	s_add_i32 m0, s16, 0xffffff80
	ds_read_b128 v[192:195], v212
	ds_read_b128 v[196:199], v212 offset:1024
	ds_read_b128 v[204:207], v212 offset:2048
	ds_read_b128 v[212:215], v212 offset:3072
	global_load_lds_dwordx4 v178, s[20:21] offset:128
	s_add_i32 m0, s16, 0x1f80
	s_nop 0
	global_load_lds_dwordx4 v144, s[20:21] offset:128
	s_barrier
	s_waitcnt lgkmcnt(0)
	v_mfma_f32_16x16x32_bf16 v[116:119], v[192:195], v[150:153], v[116:119]
	v_mfma_f32_16x16x32_bf16 v[112:115], v[204:207], v[150:153], v[112:115]
	v_mfma_f32_16x16x32_bf16 v[100:103], v[192:195], v[164:167], v[100:103]
	v_mfma_f32_16x16x32_bf16 v[96:99], v[204:207], v[164:167], v[96:99]
	v_mfma_f32_16x16x32_bf16 v[84:87], v[192:195], v[172:175], v[84:87]
	v_mfma_f32_16x16x32_bf16 v[80:83], v[204:207], v[172:175], v[80:83]
	v_mfma_f32_16x16x32_bf16 v[68:71], v[192:195], v[184:187], v[68:71]
	v_mfma_f32_16x16x32_bf16 v[64:67], v[204:207], v[184:187], v[64:67]
	v_mfma_f32_16x16x32_bf16 v[116:119], v[196:199], v[160:163], v[116:119]
	v_mfma_f32_16x16x32_bf16 v[112:115], v[212:215], v[160:163], v[112:115]
	v_mfma_f32_16x16x32_bf16 v[100:103], v[196:199], v[168:171], v[100:103]
	v_mfma_f32_16x16x32_bf16 v[96:99], v[212:215], v[168:171], v[96:99]
	v_mfma_f32_16x16x32_bf16 v[84:87], v[196:199], v[180:183], v[84:87]
	v_mfma_f32_16x16x32_bf16 v[80:83], v[212:215], v[180:183], v[80:83]
	v_mfma_f32_16x16x32_bf16 v[68:71], v[196:199], v[188:191], v[68:71]
	v_mfma_f32_16x16x32_bf16 v[64:67], v[212:215], v[188:191], v[64:67]
	s_add_i32 m0, s56, 0xffffff80
	s_barrier
	ds_read_b128 v[150:153], v159 offset:49152
	ds_read_b128 v[160:163], v159 offset:50176
	ds_read_b128 v[164:167], v159 offset:51200
	ds_read_b128 v[168:171], v159 offset:52224
	ds_read_b128 v[172:175], v159 offset:53248
	ds_read_b128 v[180:183], v159 offset:54272
	ds_read_b128 v[184:187], v159 offset:55296
	ds_read_b128 v[188:191], v159 offset:56320
	global_load_lds_dwordx4 v178, s[100:101] offset:128
	s_add_i32 m0, s57, 0xffffff80
	s_nop 0
	global_load_lds_dwordx4 v144, s[100:101] offset:128
	s_barrier
	s_waitcnt lgkmcnt(0)
	v_mfma_f32_16x16x32_bf16 v[60:63], v[128:131], v[150:153], v[60:63]
	v_mfma_f32_16x16x32_bf16 v[56:59], v[136:139], v[150:153], v[56:59]
	v_mfma_f32_16x16x32_bf16 v[44:47], v[128:131], v[164:167], v[44:47]
	v_mfma_f32_16x16x32_bf16 v[40:43], v[136:139], v[164:167], v[40:43]
	v_mfma_f32_16x16x32_bf16 v[28:31], v[128:131], v[172:175], v[28:31]
	v_mfma_f32_16x16x32_bf16 v[24:27], v[136:139], v[172:175], v[24:27]
	v_mfma_f32_16x16x32_bf16 v[12:15], v[128:131], v[184:187], v[12:15]
	v_mfma_f32_16x16x32_bf16 v[8:11], v[136:139], v[184:187], v[8:11]
	v_mfma_f32_16x16x32_bf16 v[60:63], v[132:135], v[160:163], v[60:63]
	v_mfma_f32_16x16x32_bf16 v[56:59], v[140:143], v[160:163], v[56:59]
	v_mfma_f32_16x16x32_bf16 v[44:47], v[132:135], v[168:171], v[44:47]
	v_mfma_f32_16x16x32_bf16 v[40:43], v[140:143], v[168:171], v[40:43]
	v_mfma_f32_16x16x32_bf16 v[28:31], v[132:135], v[180:183], v[28:31]
	v_mfma_f32_16x16x32_bf16 v[24:27], v[140:143], v[180:183], v[24:27]
	v_mfma_f32_16x16x32_bf16 v[12:15], v[132:135], v[188:191], v[12:15]
	v_mfma_f32_16x16x32_bf16 v[8:11], v[140:143], v[188:191], v[8:11]
	s_barrier
	s_add_u32 s16, s20, 0x80080
	s_addc_u32 s17, s21, 0
	s_add_i32 s20, s22, s28
	s_mov_b32 m0, s20
	s_nop 0
	global_load_lds_dwordx4 v178, s[16:17]
	s_add_i32 m0, s20, 0x2000
	s_nop 0
	global_load_lds_dwordx4 v144, s[16:17]
	s_waitcnt vmcnt(6)
	s_barrier
	v_mfma_f32_16x16x32_bf16 v[52:55], v[192:195], v[150:153], v[52:55]
	v_mfma_f32_16x16x32_bf16 v[48:51], v[204:207], v[150:153], v[48:51]
	v_mfma_f32_16x16x32_bf16 v[36:39], v[192:195], v[164:167], v[36:39]
	v_mfma_f32_16x16x32_bf16 v[32:35], v[204:207], v[164:167], v[32:35]
	v_mfma_f32_16x16x32_bf16 v[20:23], v[192:195], v[172:175], v[20:23]
	v_mfma_f32_16x16x32_bf16 v[16:19], v[204:207], v[172:175], v[16:19]
	v_mfma_f32_16x16x32_bf16 v[4:7], v[192:195], v[184:187], v[4:7]
	v_mfma_f32_16x16x32_bf16 v[0:3], v[204:207], v[184:187], v[0:3]
	v_mfma_f32_16x16x32_bf16 v[52:55], v[196:199], v[160:163], v[52:55]
	v_mfma_f32_16x16x32_bf16 v[48:51], v[212:215], v[160:163], v[48:51]
	v_mfma_f32_16x16x32_bf16 v[36:39], v[196:199], v[168:171], v[36:39]
	v_mfma_f32_16x16x32_bf16 v[32:35], v[212:215], v[168:171], v[32:35]
	v_mfma_f32_16x16x32_bf16 v[20:23], v[196:199], v[180:183], v[20:23]
	v_mfma_f32_16x16x32_bf16 v[16:19], v[212:215], v[180:183], v[16:19]
	v_mfma_f32_16x16x32_bf16 v[4:7], v[196:199], v[188:191], v[4:7]
	v_mfma_f32_16x16x32_bf16 v[0:3], v[212:215], v[188:191], v[0:3]
	s_add_i32 s63, s63, 2
	s_add_u32 s5, s5, 0x100
	s_addc_u32 s62, s62, 0
	s_cmp_gt_u32 s63, 29
	s_mov_b64 s[16:17], s[18:19]
	s_barrier
	s_cbranch_scc0 .LBB0_1077
	s_lshl_b32 s5, s60, 8
	s_add_i32 s12, s5, 0xfffff000
	s_ashr_i32 s12, s12, 11
	s_add_i32 s12, s12, 1
	s_cmp_lt_i32 s60, 16
	s_cselect_b32 s12, 0, s12
	v_add_u32_e32 v154, s5, v156
	v_lshl_or_b32 v152, s61, 8, v158
	s_mul_hi_i32 s15, s12, 0xc000
	s_mul_i32 s14, s12, 0xc000
	v_readlane_b32 s12, v254, 59
	v_readlane_b32 s13, v254, 63
	v_ashrrev_i32_e32 v155, 31, v154
	s_cselect_b32 s13, s12, s13
	v_readlane_b32 s12, v254, 61
	v_readlane_b32 s16, v255, 1
	v_ashrrev_i32_e32 v153, 31, v152
	v_lshlrev_b64 v[150:151], 11, v[154:155]
	s_cselect_b32 s12, s12, s16
	s_add_u32 s14, s35, s14
	v_lshl_add_u64 v[150:151], v[150:151], 0, v[152:153]
	s_addc_u32 s15, s39, s15
	v_lshlrev_b64 v[150:151], 2, v[150:151]
	v_lshl_add_u64 v[128:129], v[152:153], 2, s[14:15]
	v_lshl_add_u64 v[166:167], s[12:13], 0, v[150:151]
	global_load_dwordx4 v[140:143], v[128:129], off
	global_load_dwordx4 v[136:139], v[128:129], off offset:64
	global_load_dwordx4 v[132:135], v[128:129], off offset:512
	s_nop 0
	global_load_dwordx4 v[128:131], v[128:129], off offset:576
	v_readlane_b32 s68, v252, 37
	v_readlane_b32 s82, v252, 51
	v_readlane_b32 s83, v252, 52
	s_and_b64 vcc, exec, s[10:11]
	s_mov_b32 s61, s59
	s_mov_b32 s60, s4
	s_mov_b64 s[18:19], s[6:7]
	s_mov_b64 s[16:17], s[8:9]
	v_readlane_b32 s69, v252, 38
	v_readlane_b32 s70, v252, 39
	v_readlane_b32 s71, v252, 40
	v_readlane_b32 s72, v252, 41
	v_readlane_b32 s73, v252, 42
	v_readlane_b32 s74, v252, 43
	v_readlane_b32 s75, v252, 44
	v_readlane_b32 s76, v252, 45
	v_readlane_b32 s77, v252, 46
	v_readlane_b32 s78, v252, 47
	v_readlane_b32 s79, v252, 48
	v_readlane_b32 s80, v252, 49
	v_readlane_b32 s81, v252, 50
	s_nop 4
	v_mov_b32_e32 v145, v150
	v_add_u32_e32 v164, 0x20000, v145
	v_add_u32_e32 v165, 0x40000, v145
	v_add_u32_e32 v176, 0x60000, v145
	v_add_u32_e32 v177, 0x100000, v145
	v_add_u32_e32 v223, 0x120000, v145
	v_add_u32_e32 v248, 0x140000, v145
	v_add_u32_e32 v249, 0x160000, v145
	global_load_dwordx4 v[160:163], v145, s[12:13]
	global_load_dwordx4 v[168:171], v145, s[12:13] offset:64
	global_load_dwordx4 v[172:175], v145, s[12:13] offset:512
	global_load_dwordx4 v[180:183], v145, s[12:13] offset:576
	global_load_dwordx4 v[184:187], v164, s[12:13]
	global_load_dwordx4 v[188:191], v164, s[12:13] offset:64
	global_load_dwordx4 v[192:195], v164, s[12:13] offset:512
	global_load_dwordx4 v[196:199], v164, s[12:13] offset:576
	global_load_dwordx4 v[204:207], v165, s[12:13]
	global_load_dwordx4 v[212:215], v165, s[12:13] offset:64
	global_load_dwordx4 v[224:227], v165, s[12:13] offset:512
	global_load_dwordx4 v[228:231], v165, s[12:13] offset:576
	global_load_dwordx4 v[232:235], v176, s[12:13]
	global_load_dwordx4 v[236:239], v176, s[12:13] offset:64
	global_load_dwordx4 v[240:243], v176, s[12:13] offset:512
	global_load_dwordx4 v[244:247], v176, s[12:13] offset:576
	s_waitcnt vmcnt(15)
	v_pk_fma_f32 v[126:127], v[126:127], v[142:143], v[162:163]
	v_pk_fma_f32 v[124:125], v[124:125], v[140:141], v[160:161]
	global_store_dwordx4 v145, v[124:127], s[82:83]
	global_load_dwordx4 v[160:163], v177, s[12:13]
	s_waitcnt vmcnt(16)
	v_pk_fma_f32 v[122:123], v[122:123], v[138:139], v[170:171]
	v_pk_fma_f32 v[120:121], v[120:121], v[136:137], v[168:169]
	global_store_dwordx4 v145, v[120:123], s[82:83] offset:64
	global_load_dwordx4 v[168:171], v177, s[12:13] offset:64
	s_waitcnt vmcnt(17)
	v_pk_fma_f32 v[118:119], v[118:119], v[134:135], v[174:175]
	v_pk_fma_f32 v[116:117], v[116:117], v[132:133], v[172:173]
	global_store_dwordx4 v145, v[116:119], s[82:83] offset:512
	global_load_dwordx4 v[172:175], v177, s[12:13] offset:512
	s_waitcnt vmcnt(18)
	v_pk_fma_f32 v[114:115], v[114:115], v[130:131], v[182:183]
	v_pk_fma_f32 v[112:113], v[112:113], v[128:129], v[180:181]
	global_store_dwordx4 v145, v[112:115], s[82:83] offset:576
	global_load_dwordx4 v[180:183], v177, s[12:13] offset:576
	s_waitcnt vmcnt(19)
	v_pk_fma_f32 v[110:111], v[110:111], v[142:143], v[186:187]
	v_pk_fma_f32 v[108:109], v[108:109], v[140:141], v[184:185]
	global_store_dwordx4 v164, v[108:111], s[82:83]
	global_load_dwordx4 v[184:187], v223, s[12:13]
	s_waitcnt vmcnt(20)
	v_pk_fma_f32 v[106:107], v[106:107], v[138:139], v[190:191]
	v_pk_fma_f32 v[104:105], v[104:105], v[136:137], v[188:189]
	global_store_dwordx4 v164, v[104:107], s[82:83] offset:64
	global_load_dwordx4 v[188:191], v223, s[12:13] offset:64
	s_waitcnt vmcnt(21)
	v_pk_fma_f32 v[102:103], v[102:103], v[134:135], v[194:195]
	v_pk_fma_f32 v[100:101], v[100:101], v[132:133], v[192:193]
	global_store_dwordx4 v164, v[100:103], s[82:83] offset:512
	global_load_dwordx4 v[192:195], v223, s[12:13] offset:512
	s_waitcnt vmcnt(22)
	v_pk_fma_f32 v[98:99], v[98:99], v[130:131], v[198:199]
	v_pk_fma_f32 v[96:97], v[96:97], v[128:129], v[196:197]
	global_store_dwordx4 v164, v[96:99], s[82:83] offset:576
	global_load_dwordx4 v[196:199], v223, s[12:13] offset:576
	s_waitcnt vmcnt(23)
	v_pk_fma_f32 v[94:95], v[94:95], v[142:143], v[206:207]
	v_pk_fma_f32 v[92:93], v[92:93], v[140:141], v[204:205]
	global_store_dwordx4 v165, v[92:95], s[82:83]
	global_load_dwordx4 v[204:207], v248, s[12:13]
	s_waitcnt vmcnt(24)
	v_pk_fma_f32 v[90:91], v[90:91], v[138:139], v[214:215]
	v_pk_fma_f32 v[88:89], v[88:89], v[136:137], v[212:213]
	global_store_dwordx4 v165, v[88:91], s[82:83] offset:64
	global_load_dwordx4 v[212:215], v248, s[12:13] offset:64
	s_waitcnt vmcnt(25)
	v_pk_fma_f32 v[86:87], v[86:87], v[134:135], v[226:227]
	v_pk_fma_f32 v[84:85], v[84:85], v[132:133], v[224:225]
	global_store_dwordx4 v165, v[84:87], s[82:83] offset:512
	global_load_dwordx4 v[224:227], v248, s[12:13] offset:512
	s_waitcnt vmcnt(26)
	v_pk_fma_f32 v[82:83], v[82:83], v[130:131], v[230:231]
	v_pk_fma_f32 v[80:81], v[80:81], v[128:129], v[228:229]
	global_store_dwordx4 v165, v[80:83], s[82:83] offset:576
	global_load_dwordx4 v[228:231], v248, s[12:13] offset:576
	s_waitcnt vmcnt(27)
	v_pk_fma_f32 v[78:79], v[78:79], v[142:143], v[234:235]
	v_pk_fma_f32 v[76:77], v[76:77], v[140:141], v[232:233]
	global_store_dwordx4 v176, v[76:79], s[82:83]
	global_load_dwordx4 v[232:235], v249, s[12:13]
	s_waitcnt vmcnt(28)
	v_pk_fma_f32 v[74:75], v[74:75], v[138:139], v[238:239]
	v_pk_fma_f32 v[72:73], v[72:73], v[136:137], v[236:237]
	global_store_dwordx4 v176, v[72:75], s[82:83] offset:64
	global_load_dwordx4 v[236:239], v249, s[12:13] offset:64
	s_waitcnt vmcnt(29)
	v_pk_fma_f32 v[70:71], v[70:71], v[134:135], v[242:243]
	v_pk_fma_f32 v[68:69], v[68:69], v[132:133], v[240:241]
	global_store_dwordx4 v176, v[68:71], s[82:83] offset:512
	global_load_dwordx4 v[240:243], v249, s[12:13] offset:512
	s_waitcnt vmcnt(30)
	v_pk_fma_f32 v[66:67], v[66:67], v[130:131], v[246:247]
	v_pk_fma_f32 v[64:65], v[64:65], v[128:129], v[244:245]
	global_store_dwordx4 v176, v[64:67], s[82:83] offset:576
	global_load_dwordx4 v[244:247], v249, s[12:13] offset:576
	s_waitcnt vmcnt(30)
	v_pk_fma_f32 v[62:63], v[62:63], v[142:143], v[162:163]
	v_pk_fma_f32 v[60:61], v[60:61], v[140:141], v[160:161]
	global_store_dwordx4 v177, v[60:63], s[82:83]
	s_waitcnt vmcnt(29)
	v_pk_fma_f32 v[58:59], v[58:59], v[138:139], v[170:171]
	v_pk_fma_f32 v[56:57], v[56:57], v[136:137], v[168:169]
	global_store_dwordx4 v177, v[56:59], s[82:83] offset:64
	s_waitcnt vmcnt(28)
	v_pk_fma_f32 v[54:55], v[54:55], v[134:135], v[174:175]
	v_pk_fma_f32 v[52:53], v[52:53], v[132:133], v[172:173]
	global_store_dwordx4 v177, v[52:55], s[82:83] offset:512
	s_waitcnt vmcnt(27)
	v_pk_fma_f32 v[50:51], v[50:51], v[130:131], v[182:183]
	v_pk_fma_f32 v[48:49], v[48:49], v[128:129], v[180:181]
	global_store_dwordx4 v177, v[48:51], s[82:83] offset:576
	s_waitcnt vmcnt(26)
	v_pk_fma_f32 v[46:47], v[46:47], v[142:143], v[186:187]
	v_pk_fma_f32 v[44:45], v[44:45], v[140:141], v[184:185]
	global_store_dwordx4 v223, v[44:47], s[82:83]
	s_waitcnt vmcnt(25)
	v_pk_fma_f32 v[42:43], v[42:43], v[138:139], v[190:191]
	v_pk_fma_f32 v[40:41], v[40:41], v[136:137], v[188:189]
	global_store_dwordx4 v223, v[40:43], s[82:83] offset:64
	s_waitcnt vmcnt(24)
	v_pk_fma_f32 v[38:39], v[38:39], v[134:135], v[194:195]
	v_pk_fma_f32 v[36:37], v[36:37], v[132:133], v[192:193]
	global_store_dwordx4 v223, v[36:39], s[82:83] offset:512
	s_waitcnt vmcnt(23)
	v_pk_fma_f32 v[34:35], v[34:35], v[130:131], v[198:199]
	v_pk_fma_f32 v[32:33], v[32:33], v[128:129], v[196:197]
	global_store_dwordx4 v223, v[32:35], s[82:83] offset:576
	s_waitcnt vmcnt(22)
	v_pk_fma_f32 v[30:31], v[30:31], v[142:143], v[206:207]
	v_pk_fma_f32 v[28:29], v[28:29], v[140:141], v[204:205]
	global_store_dwordx4 v248, v[28:31], s[82:83]
	s_waitcnt vmcnt(21)
	v_pk_fma_f32 v[26:27], v[26:27], v[138:139], v[214:215]
	v_pk_fma_f32 v[24:25], v[24:25], v[136:137], v[212:213]
	global_store_dwordx4 v248, v[24:27], s[82:83] offset:64
	s_waitcnt vmcnt(20)
	v_pk_fma_f32 v[22:23], v[22:23], v[134:135], v[226:227]
	v_pk_fma_f32 v[20:21], v[20:21], v[132:133], v[224:225]
	global_store_dwordx4 v248, v[20:23], s[82:83] offset:512
	s_waitcnt vmcnt(19)
	v_pk_fma_f32 v[18:19], v[18:19], v[130:131], v[230:231]
	v_pk_fma_f32 v[16:17], v[16:17], v[128:129], v[228:229]
	global_store_dwordx4 v248, v[16:19], s[82:83] offset:576
	s_waitcnt vmcnt(18)
	v_pk_fma_f32 v[14:15], v[14:15], v[142:143], v[234:235]
	v_pk_fma_f32 v[12:13], v[12:13], v[140:141], v[232:233]
	global_store_dwordx4 v249, v[12:15], s[82:83]
	s_waitcnt vmcnt(17)
	v_pk_fma_f32 v[10:11], v[10:11], v[138:139], v[238:239]
	v_pk_fma_f32 v[8:9], v[8:9], v[136:137], v[236:237]
	global_store_dwordx4 v249, v[8:11], s[82:83] offset:64
	s_waitcnt vmcnt(16)
	v_pk_fma_f32 v[6:7], v[6:7], v[134:135], v[242:243]
	v_pk_fma_f32 v[4:5], v[4:5], v[132:133], v[240:241]
	global_store_dwordx4 v249, v[4:7], s[82:83] offset:512
	s_waitcnt vmcnt(15)
	v_pk_fma_f32 v[2:3], v[2:3], v[130:131], v[246:247]
	v_pk_fma_f32 v[0:1], v[0:1], v[128:129], v[244:245]
	global_store_dwordx4 v249, v[0:3], s[82:83] offset:576
	s_mov_b64 s[14:15], 0x160000
	s_cbranch_vccz .LBB0_1074
	s_waitcnt vmcnt(0)
	s_mov_b32 s4, s86
	s_cmp_gt_u32 s4, 3
	s_mov_b32 s34, 0x10000
	s_movk_i32 s57, 0x404
	s_cbranch_scc1 .LBB0_1081
	s_barrier

.LBB0_1198:
	s_add_u32 s70, s8, 0xfff80080
	s_addc_u32 s71, s9, -1
	s_add_i32 s77, 0, 0x10000
	v_add_u32_e32 v140, s77, v225
	ds_read_b128 v[128:131], v140
	ds_read_b128 v[132:135], v140 offset:1024
	ds_read_b128 v[136:139], v140 offset:2048
	ds_read_b128 v[140:143], v140 offset:3072
	s_cmp_eq_u32 s76, 28
	s_cselect_b32 s73, s5, s71
	s_cselect_b32 s72, s4, s70
	s_cselect_b32 s71, s7, s75
	s_cselect_b32 s70, s6, s35
	s_add_i32 m0, s84, 0xc000
	ds_read_b128 v[144:147], v226
	ds_read_b128 v[148:151], v226 offset:1024
	ds_read_b128 v[152:155], v226 offset:2048
	ds_read_b128 v[156:159], v226 offset:3072
	ds_read_b128 v[160:163], v226 offset:4096
	ds_read_b128 v[164:167], v226 offset:5120
	ds_read_b128 v[168:171], v226 offset:6144
	ds_read_b128 v[172:175], v226 offset:7168
	global_load_lds_dwordx4 v190, s[8:9]
	s_add_i32 m0, s84, 0xe000
	s_nop 0
	global_load_lds_dwordx4 v188, s[8:9]
	s_waitcnt lgkmcnt(8)
	s_barrier
	s_waitcnt lgkmcnt(0)
	v_mfma_f32_16x16x32_bf16 v[124:127], v[128:131], v[144:147], v[124:127]
	v_mfma_f32_16x16x32_bf16 v[60:63], v[136:139], v[144:147], v[60:63]
	v_mfma_f32_16x16x32_bf16 v[116:119], v[128:131], v[152:155], v[116:119]
	v_mfma_f32_16x16x32_bf16 v[52:55], v[136:139], v[152:155], v[52:55]
	v_mfma_f32_16x16x32_bf16 v[108:111], v[128:131], v[160:163], v[108:111]
	v_mfma_f32_16x16x32_bf16 v[44:47], v[136:139], v[160:163], v[44:47]
	v_mfma_f32_16x16x32_bf16 v[100:103], v[128:131], v[168:171], v[100:103]
	v_mfma_f32_16x16x32_bf16 v[36:39], v[136:139], v[168:171], v[36:39]
	v_mfma_f32_16x16x32_bf16 v[124:127], v[132:135], v[148:151], v[124:127]
	v_mfma_f32_16x16x32_bf16 v[60:63], v[140:143], v[148:151], v[60:63]
	v_mfma_f32_16x16x32_bf16 v[116:119], v[132:135], v[156:159], v[116:119]
	v_mfma_f32_16x16x32_bf16 v[52:55], v[140:143], v[156:159], v[52:55]
	v_mfma_f32_16x16x32_bf16 v[108:111], v[132:135], v[164:167], v[108:111]
	v_mfma_f32_16x16x32_bf16 v[44:47], v[140:143], v[164:167], v[44:47]
	v_mfma_f32_16x16x32_bf16 v[100:103], v[132:135], v[172:175], v[100:103]
	v_mfma_f32_16x16x32_bf16 v[36:39], v[140:143], v[172:175], v[36:39]
	s_barrier
	s_add_i32 vcc_lo, 0, 0x14000
	v_add_u32_e32 v176, vcc_lo, v225
	s_add_i32 s77, s77, s24
	ds_read_b128 v[192:195], v176
	ds_read_b128 v[196:199], v176 offset:1024
	ds_read_b128 v[204:207], v176 offset:2048
	ds_read_b128 v[212:215], v176 offset:3072
	s_mov_b32 m0, s77
	s_nop 0
	global_load_lds_dwordx4 v182, s[70:71]
	s_add_i32 m0, s77, 0x2000
	s_nop 0
	global_load_lds_dwordx4 v186, s[70:71]
	s_barrier
	s_waitcnt lgkmcnt(0)
	v_mfma_f32_16x16x32_bf16 v[120:123], v[192:195], v[144:147], v[120:123]
	v_mfma_f32_16x16x32_bf16 v[56:59], v[204:207], v[144:147], v[56:59]
	v_mfma_f32_16x16x32_bf16 v[112:115], v[192:195], v[152:155], v[112:115]
	v_mfma_f32_16x16x32_bf16 v[48:51], v[204:207], v[152:155], v[48:51]
	v_mfma_f32_16x16x32_bf16 v[104:107], v[192:195], v[160:163], v[104:107]
	v_mfma_f32_16x16x32_bf16 v[40:43], v[204:207], v[160:163], v[40:43]
	v_mfma_f32_16x16x32_bf16 v[96:99], v[192:195], v[168:171], v[96:99]
	v_mfma_f32_16x16x32_bf16 v[32:35], v[204:207], v[168:171], v[32:35]
	v_mfma_f32_16x16x32_bf16 v[120:123], v[196:199], v[148:151], v[120:123]
	v_mfma_f32_16x16x32_bf16 v[56:59], v[212:215], v[148:151], v[56:59]
	v_mfma_f32_16x16x32_bf16 v[112:115], v[196:199], v[156:159], v[112:115]
	v_mfma_f32_16x16x32_bf16 v[48:51], v[212:215], v[156:159], v[48:51]
	v_mfma_f32_16x16x32_bf16 v[104:107], v[196:199], v[164:167], v[104:107]
	v_mfma_f32_16x16x32_bf16 v[40:43], v[212:215], v[164:167], v[40:43]
	v_mfma_f32_16x16x32_bf16 v[96:99], v[196:199], v[172:175], v[96:99]
	v_mfma_f32_16x16x32_bf16 v[32:35], v[212:215], v[172:175], v[32:35]
	s_mov_b32 m0, s84
	s_mov_b64 s[100:101], s[72:73]
	s_barrier
	ds_read_b128 v[144:147], v226 offset:16384
	ds_read_b128 v[148:151], v226 offset:17408
	ds_read_b128 v[152:155], v226 offset:18432
	ds_read_b128 v[156:159], v226 offset:19456
	ds_read_b128 v[160:163], v226 offset:20480
	ds_read_b128 v[164:167], v226 offset:21504
	ds_read_b128 v[168:171], v226 offset:22528
	ds_read_b128 v[172:175], v226 offset:23552
	global_load_lds_dwordx4 v180, s[72:73]
	s_mov_b32 m0, s85
	s_mov_b64 s[100:101], s[72:73]
	global_load_lds_dwordx4 v184, s[72:73]
	s_barrier
	s_waitcnt lgkmcnt(0)
	v_mfma_f32_16x16x32_bf16 v[92:95], v[128:131], v[144:147], v[92:95]
	v_mfma_f32_16x16x32_bf16 v[28:31], v[136:139], v[144:147], v[28:31]
	v_mfma_f32_16x16x32_bf16 v[84:87], v[128:131], v[152:155], v[84:87]
	v_mfma_f32_16x16x32_bf16 v[20:23], v[136:139], v[152:155], v[20:23]
	v_mfma_f32_16x16x32_bf16 v[76:79], v[128:131], v[160:163], v[76:79]
	v_mfma_f32_16x16x32_bf16 v[12:15], v[136:139], v[160:163], v[12:15]
	v_mfma_f32_16x16x32_bf16 v[68:71], v[128:131], v[168:171], v[68:71]
	v_mfma_f32_16x16x32_bf16 v[4:7], v[136:139], v[168:171], v[4:7]
	v_mfma_f32_16x16x32_bf16 v[92:95], v[132:135], v[148:151], v[92:95]
	v_mfma_f32_16x16x32_bf16 v[28:31], v[140:143], v[148:151], v[28:31]
	v_mfma_f32_16x16x32_bf16 v[84:87], v[132:135], v[156:159], v[84:87]
	v_mfma_f32_16x16x32_bf16 v[20:23], v[140:143], v[156:159], v[20:23]
	v_mfma_f32_16x16x32_bf16 v[76:79], v[132:135], v[164:167], v[76:79]
	v_mfma_f32_16x16x32_bf16 v[12:15], v[140:143], v[164:167], v[12:15]
	v_mfma_f32_16x16x32_bf16 v[68:71], v[132:135], v[172:175], v[68:71]
	v_mfma_f32_16x16x32_bf16 v[4:7], v[140:143], v[172:175], v[4:7]
	s_barrier
	s_add_u32 s78, s70, 0x80000
	s_addc_u32 s79, s71, 0
	s_add_i32 s77, vcc_lo, s24
	s_mov_b32 m0, s77
	s_nop 0
	global_load_lds_dwordx4 v182, s[78:79]
	s_add_i32 m0, s77, 0x2000
	s_nop 0
	global_load_lds_dwordx4 v186, s[78:79]
	s_waitcnt vmcnt(6)
	s_barrier
	v_mfma_f32_16x16x32_bf16 v[88:91], v[192:195], v[144:147], v[88:91]
	v_mfma_f32_16x16x32_bf16 v[24:27], v[204:207], v[144:147], v[24:27]
	v_mfma_f32_16x16x32_bf16 v[80:83], v[192:195], v[152:155], v[80:83]
	v_mfma_f32_16x16x32_bf16 v[16:19], v[204:207], v[152:155], v[16:19]
	v_mfma_f32_16x16x32_bf16 v[72:75], v[192:195], v[160:163], v[72:75]
	v_mfma_f32_16x16x32_bf16 v[8:11], v[204:207], v[160:163], v[8:11]
	v_mfma_f32_16x16x32_bf16 v[64:67], v[192:195], v[168:171], v[64:67]
	v_mfma_f32_16x16x32_bf16 v[0:3], v[204:207], v[168:171], v[0:3]
	v_mfma_f32_16x16x32_bf16 v[88:91], v[196:199], v[148:151], v[88:91]
	v_mfma_f32_16x16x32_bf16 v[24:27], v[212:215], v[148:151], v[24:27]
	v_mfma_f32_16x16x32_bf16 v[80:83], v[196:199], v[156:159], v[80:83]
	v_mfma_f32_16x16x32_bf16 v[16:19], v[212:215], v[156:159], v[16:19]
	v_mfma_f32_16x16x32_bf16 v[72:75], v[196:199], v[164:167], v[72:75]
	v_mfma_f32_16x16x32_bf16 v[8:11], v[212:215], v[164:167], v[8:11]
	v_mfma_f32_16x16x32_bf16 v[64:67], v[196:199], v[172:175], v[64:67]
	v_mfma_f32_16x16x32_bf16 v[0:3], v[212:215], v[172:175], v[0:3]
	s_add_i32 s77, 0, 0x18000
	v_add_u32_e32 v140, s77, v225
	s_barrier
	ds_read_b128 v[128:131], v140
	ds_read_b128 v[132:135], v140 offset:1024
	ds_read_b128 v[136:139], v140 offset:2048
	ds_read_b128 v[140:143], v140 offset:3072
	s_add_u32 s72, s72, 0x80000
	s_addc_u32 s73, s73, 0
	s_mov_b32 m0, s86
	ds_read_b128 v[144:147], v226 offset:32768
	ds_read_b128 v[148:151], v226 offset:33792
	ds_read_b128 v[152:155], v226 offset:34816
	ds_read_b128 v[156:159], v226 offset:35840
	ds_read_b128 v[160:163], v226 offset:36864
	ds_read_b128 v[164:167], v226 offset:37888
	ds_read_b128 v[168:171], v226 offset:38912
	ds_read_b128 v[172:175], v226 offset:39936
	global_load_lds_dwordx4 v180, s[72:73]
	s_mov_b32 m0, s87
	s_nop 0
	global_load_lds_dwordx4 v184, s[72:73]
	s_waitcnt lgkmcnt(8)
	s_barrier
	s_waitcnt lgkmcnt(0)
	v_mfma_f32_16x16x32_bf16 v[124:127], v[128:131], v[144:147], v[124:127]
	v_mfma_f32_16x16x32_bf16 v[60:63], v[136:139], v[144:147], v[60:63]
	v_mfma_f32_16x16x32_bf16 v[116:119], v[128:131], v[152:155], v[116:119]
	v_mfma_f32_16x16x32_bf16 v[52:55], v[136:139], v[152:155], v[52:55]
	v_mfma_f32_16x16x32_bf16 v[108:111], v[128:131], v[160:163], v[108:111]
	v_mfma_f32_16x16x32_bf16 v[44:47], v[136:139], v[160:163], v[44:47]
	v_mfma_f32_16x16x32_bf16 v[100:103], v[128:131], v[168:171], v[100:103]
	v_mfma_f32_16x16x32_bf16 v[36:39], v[136:139], v[168:171], v[36:39]
	v_mfma_f32_16x16x32_bf16 v[124:127], v[132:135], v[148:151], v[124:127]
	v_mfma_f32_16x16x32_bf16 v[60:63], v[140:143], v[148:151], v[60:63]
	v_mfma_f32_16x16x32_bf16 v[116:119], v[132:135], v[156:159], v[116:119]
	v_mfma_f32_16x16x32_bf16 v[52:55], v[140:143], v[156:159], v[52:55]
	v_mfma_f32_16x16x32_bf16 v[108:111], v[132:135], v[164:167], v[108:111]
	v_mfma_f32_16x16x32_bf16 v[44:47], v[140:143], v[164:167], v[44:47]
	v_mfma_f32_16x16x32_bf16 v[100:103], v[132:135], v[172:175], v[100:103]
	v_mfma_f32_16x16x32_bf16 v[36:39], v[140:143], v[172:175], v[36:39]
	s_barrier
	s_add_i32 s72, 0, 0x1c000
	s_add_i32 s73, s77, s24
	v_add_u32_e32 v178, s72, v225
	s_add_i32 m0, s73, 0xffffff80
	ds_read_b128 v[192:195], v178
	ds_read_b128 v[196:199], v178 offset:1024
	ds_read_b128 v[204:207], v178 offset:2048
	ds_read_b128 v[212:215], v178 offset:3072
	global_load_lds_dwordx4 v182, s[70:71] offset:128
	s_add_i32 m0, s73, 0x1f80
	s_nop 0
	global_load_lds_dwordx4 v186, s[70:71] offset:128
	s_barrier
	s_waitcnt lgkmcnt(0)
	v_mfma_f32_16x16x32_bf16 v[120:123], v[192:195], v[144:147], v[120:123]
	v_mfma_f32_16x16x32_bf16 v[56:59], v[204:207], v[144:147], v[56:59]
	v_mfma_f32_16x16x32_bf16 v[112:115], v[192:195], v[152:155], v[112:115]
	v_mfma_f32_16x16x32_bf16 v[48:51], v[204:207], v[152:155], v[48:51]
	v_mfma_f32_16x16x32_bf16 v[104:107], v[192:195], v[160:163], v[104:107]
	v_mfma_f32_16x16x32_bf16 v[40:43], v[204:207], v[160:163], v[40:43]
	v_mfma_f32_16x16x32_bf16 v[96:99], v[192:195], v[168:171], v[96:99]
	v_mfma_f32_16x16x32_bf16 v[32:35], v[204:207], v[168:171], v[32:35]
	v_mfma_f32_16x16x32_bf16 v[120:123], v[196:199], v[148:151], v[120:123]
	v_mfma_f32_16x16x32_bf16 v[56:59], v[212:215], v[148:151], v[56:59]
	v_mfma_f32_16x16x32_bf16 v[112:115], v[196:199], v[156:159], v[112:115]
	v_mfma_f32_16x16x32_bf16 v[48:51], v[212:215], v[156:159], v[48:51]
	v_mfma_f32_16x16x32_bf16 v[104:107], v[196:199], v[164:167], v[104:107]
	v_mfma_f32_16x16x32_bf16 v[40:43], v[212:215], v[164:167], v[40:43]
	v_mfma_f32_16x16x32_bf16 v[96:99], v[196:199], v[172:175], v[96:99]
	v_mfma_f32_16x16x32_bf16 v[32:35], v[212:215], v[172:175], v[32:35]
	s_add_i32 m0, s59, 0xffffff80
	s_barrier
	ds_read_b128 v[144:147], v226 offset:49152
	ds_read_b128 v[148:151], v226 offset:50176
	ds_read_b128 v[152:155], v226 offset:51200
	ds_read_b128 v[156:159], v226 offset:52224
	ds_read_b128 v[160:163], v226 offset:53248
	ds_read_b128 v[164:167], v226 offset:54272
	ds_read_b128 v[168:171], v226 offset:55296
	ds_read_b128 v[172:175], v226 offset:56320
	global_load_lds_dwordx4 v180, s[100:101] offset:128
	s_add_i32 m0, s20, 0xffffff80
	s_nop 0
	global_load_lds_dwordx4 v184, s[100:101] offset:128
	s_barrier
	s_waitcnt lgkmcnt(0)
	v_mfma_f32_16x16x32_bf16 v[92:95], v[128:131], v[144:147], v[92:95]
	v_mfma_f32_16x16x32_bf16 v[28:31], v[136:139], v[144:147], v[28:31]
	v_mfma_f32_16x16x32_bf16 v[84:87], v[128:131], v[152:155], v[84:87]
	v_mfma_f32_16x16x32_bf16 v[20:23], v[136:139], v[152:155], v[20:23]
	v_mfma_f32_16x16x32_bf16 v[76:79], v[128:131], v[160:163], v[76:79]
	v_mfma_f32_16x16x32_bf16 v[12:15], v[136:139], v[160:163], v[12:15]
	v_mfma_f32_16x16x32_bf16 v[68:71], v[128:131], v[168:171], v[68:71]
	v_mfma_f32_16x16x32_bf16 v[4:7], v[136:139], v[168:171], v[4:7]
	v_mfma_f32_16x16x32_bf16 v[92:95], v[132:135], v[148:151], v[92:95]
	v_mfma_f32_16x16x32_bf16 v[28:31], v[140:143], v[148:151], v[28:31]
	v_mfma_f32_16x16x32_bf16 v[84:87], v[132:135], v[156:159], v[84:87]
	v_mfma_f32_16x16x32_bf16 v[20:23], v[140:143], v[156:159], v[20:23]
	v_mfma_f32_16x16x32_bf16 v[76:79], v[132:135], v[164:167], v[76:79]
	v_mfma_f32_16x16x32_bf16 v[12:15], v[140:143], v[164:167], v[12:15]
	v_mfma_f32_16x16x32_bf16 v[68:71], v[132:135], v[172:175], v[68:71]
	v_mfma_f32_16x16x32_bf16 v[4:7], v[140:143], v[172:175], v[4:7]
	s_barrier
	s_add_u32 s70, s70, 0x80080
	s_addc_u32 s71, s71, 0
	s_add_i32 s72, s72, s24
	s_mov_b32 m0, s72
	s_nop 0
	global_load_lds_dwordx4 v182, s[70:71]
	s_add_i32 m0, s72, 0x2000
	s_nop 0
	global_load_lds_dwordx4 v186, s[70:71]
	s_waitcnt vmcnt(6)
	s_barrier
	v_mfma_f32_16x16x32_bf16 v[88:91], v[192:195], v[144:147], v[88:91]
	v_mfma_f32_16x16x32_bf16 v[24:27], v[204:207], v[144:147], v[24:27]
	v_mfma_f32_16x16x32_bf16 v[80:83], v[192:195], v[152:155], v[80:83]
	v_mfma_f32_16x16x32_bf16 v[16:19], v[204:207], v[152:155], v[16:19]
	v_mfma_f32_16x16x32_bf16 v[72:75], v[192:195], v[160:163], v[72:75]
	v_mfma_f32_16x16x32_bf16 v[8:11], v[204:207], v[160:163], v[8:11]
	v_mfma_f32_16x16x32_bf16 v[64:67], v[192:195], v[168:171], v[64:67]
	v_mfma_f32_16x16x32_bf16 v[0:3], v[204:207], v[168:171], v[0:3]
	v_mfma_f32_16x16x32_bf16 v[88:91], v[196:199], v[148:151], v[88:91]
	v_mfma_f32_16x16x32_bf16 v[24:27], v[212:215], v[148:151], v[24:27]
	v_mfma_f32_16x16x32_bf16 v[80:83], v[196:199], v[156:159], v[80:83]
	v_mfma_f32_16x16x32_bf16 v[16:19], v[212:215], v[156:159], v[16:19]
	v_mfma_f32_16x16x32_bf16 v[72:75], v[196:199], v[164:167], v[72:75]
	v_mfma_f32_16x16x32_bf16 v[8:11], v[212:215], v[164:167], v[8:11]
	v_mfma_f32_16x16x32_bf16 v[64:67], v[196:199], v[172:175], v[64:67]
	v_mfma_f32_16x16x32_bf16 v[0:3], v[212:215], v[172:175], v[0:3]
	s_add_i32 s76, s76, 2
	s_add_u32 s35, s35, 0x100
	s_addc_u32 s75, s75, 0
	s_add_u32 s8, s8, 0x100
	s_addc_u32 s9, s9, 0
	s_cmp_gt_u32 s76, 29
	s_barrier
	s_cbranch_scc0 .LBB0_1198
	v_mov_b32_e32 v140, v224
	v_mov_b32_e32 v194, v223
	v_readlane_b32 s4, v255, 16
	v_lshlrev_b32_e32 v227, 6, v140
	v_cmp_lt_i32_e32 vcc, 14, v194
	v_add_u32_e32 v141, s4, v227
	s_mov_b64 s[4:5], 0
	s_and_saveexec_b64 s[6:7], vcc
	s_xor_b64 s[6:7], exec, s[6:7]
	s_cbranch_execz .LBB0_1203
	v_cmp_eq_u32_e32 vcc, 15, v194
	s_and_saveexec_b64 s[8:9], vcc
	s_mov_b64 s[4:5], exec
	ds_write_b128 v141, v[100:103] offset:256
	s_or_b64 exec, exec, s[8:9]
	s_and_b64 s[4:5], s[4:5], exec

.LBB0_1363:
	s_add_u32 s16, s14, 0x100
	s_addc_u32 s17, s15, 0
	s_add_i32 s68, 0, 0x10000
	v_add_u32_e32 v76, s68, v153
	ds_read_b128 v[48:51], v76
	ds_read_b128 v[68:71], v76 offset:1024
	ds_read_b128 v[72:75], v76 offset:2048
	ds_read_b128 v[76:79], v76 offset:3072
	s_cmpk_eq_i32 s67, 0x52
	s_cselect_b32 s21, s11, s17
	s_cselect_b32 s20, s10, s16
	s_cselect_b32 s19, s13, s66
	s_cselect_b32 s18, s12, s63
	v_lshl_add_u64 v[150:151], s[14:15], 0, v[148:149]
	s_add_i32 m0, s29, 0xc000
	ds_read_b128 v[156:159], v155
	ds_read_b128 v[160:163], v155 offset:1024
	ds_read_b128 v[164:167], v155 offset:2048
	ds_read_b128 v[168:171], v155 offset:3072
	ds_read_b128 v[172:175], v155 offset:4096
	ds_read_b128 v[180:183], v155 offset:5120
	ds_read_b128 v[184:187], v155 offset:6144
	ds_read_b128 v[188:191], v155 offset:7168
	global_load_lds_dwordx4 v[150:151], off
	v_lshl_add_u64 v[150:151], s[14:15], 0, v[146:147]
	s_add_i32 m0, s29, 0xe000
	s_nop 0
	global_load_lds_dwordx4 v[150:151], off
	s_waitcnt lgkmcnt(8)
	s_barrier
	s_waitcnt lgkmcnt(0)
	v_mfma_f32_16x16x32_bf16 v[140:143], v[48:51], v[156:159], v[140:143]
	v_mfma_f32_16x16x32_bf16 v[136:139], v[72:75], v[156:159], v[136:139]
	v_mfma_f32_16x16x32_bf16 v[124:127], v[48:51], v[164:167], v[124:127]
	v_mfma_f32_16x16x32_bf16 v[120:123], v[72:75], v[164:167], v[120:123]
	v_mfma_f32_16x16x32_bf16 v[116:119], v[48:51], v[172:175], v[116:119]
	v_mfma_f32_16x16x32_bf16 v[112:115], v[72:75], v[172:175], v[112:115]
	v_mfma_f32_16x16x32_bf16 v[100:103], v[48:51], v[184:187], v[100:103]
	v_mfma_f32_16x16x32_bf16 v[96:99], v[72:75], v[184:187], v[96:99]
	v_mfma_f32_16x16x32_bf16 v[140:143], v[68:71], v[160:163], v[140:143]
	v_mfma_f32_16x16x32_bf16 v[136:139], v[76:79], v[160:163], v[136:139]
	v_mfma_f32_16x16x32_bf16 v[124:127], v[68:71], v[168:171], v[124:127]
	v_mfma_f32_16x16x32_bf16 v[120:123], v[76:79], v[168:171], v[120:123]
	v_mfma_f32_16x16x32_bf16 v[116:119], v[68:71], v[180:183], v[116:119]
	v_mfma_f32_16x16x32_bf16 v[112:115], v[76:79], v[180:183], v[112:115]
	v_mfma_f32_16x16x32_bf16 v[100:103], v[68:71], v[188:191], v[100:103]
	v_mfma_f32_16x16x32_bf16 v[96:99], v[76:79], v[188:191], v[96:99]
	s_barrier
	s_add_i32 s69, 0, 0x14000
	v_add_u32_e32 v150, s69, v153
	s_add_i32 s14, s68, s28
	ds_read_b128 v[192:195], v150
	ds_read_b128 v[196:199], v150 offset:1024
	ds_read_b128 v[204:207], v150 offset:2048
	ds_read_b128 v[212:215], v150 offset:3072
	s_mov_b32 m0, s14
	s_nop 0
	global_load_lds_dwordx4 v178, s[18:19]
	s_add_i32 m0, s14, 0x2000
	s_nop 0
	global_load_lds_dwordx4 v144, s[18:19]
	s_barrier
	s_waitcnt lgkmcnt(0)
	v_mfma_f32_16x16x32_bf16 v[132:135], v[192:195], v[156:159], v[132:135]
	v_mfma_f32_16x16x32_bf16 v[128:131], v[204:207], v[156:159], v[128:131]
	v_mfma_f32_16x16x32_bf16 v[108:111], v[192:195], v[164:167], v[108:111]
	v_mfma_f32_16x16x32_bf16 v[104:107], v[204:207], v[164:167], v[104:107]
	v_mfma_f32_16x16x32_bf16 v[92:95], v[192:195], v[172:175], v[92:95]
	v_mfma_f32_16x16x32_bf16 v[88:91], v[204:207], v[172:175], v[88:91]
	v_mfma_f32_16x16x32_bf16 v[84:87], v[192:195], v[184:187], v[84:87]
	v_mfma_f32_16x16x32_bf16 v[80:83], v[204:207], v[184:187], v[80:83]
	v_mfma_f32_16x16x32_bf16 v[132:135], v[196:199], v[160:163], v[132:135]
	v_mfma_f32_16x16x32_bf16 v[128:131], v[212:215], v[160:163], v[128:131]
	v_mfma_f32_16x16x32_bf16 v[108:111], v[196:199], v[168:171], v[108:111]
	v_mfma_f32_16x16x32_bf16 v[104:107], v[212:215], v[168:171], v[104:107]
	v_mfma_f32_16x16x32_bf16 v[92:95], v[196:199], v[180:183], v[92:95]
	v_mfma_f32_16x16x32_bf16 v[88:91], v[212:215], v[180:183], v[88:91]
	v_mfma_f32_16x16x32_bf16 v[84:87], v[196:199], v[188:191], v[84:87]
	v_mfma_f32_16x16x32_bf16 v[80:83], v[212:215], v[188:191], v[80:83]
	s_mov_b32 m0, s29
	s_mov_b64 s[100:101], s[20:21]
	s_barrier
	ds_read_b128 v[156:159], v155 offset:16384
	ds_read_b128 v[160:163], v155 offset:17408
	ds_read_b128 v[164:167], v155 offset:18432
	ds_read_b128 v[168:171], v155 offset:19456
	ds_read_b128 v[172:175], v155 offset:20480
	ds_read_b128 v[180:183], v155 offset:21504
	ds_read_b128 v[184:187], v155 offset:22528
	ds_read_b128 v[188:191], v155 offset:23552
	global_load_lds_dwordx4 v178, s[20:21]
	s_mov_b32 m0, s30
	s_mov_b64 s[100:101], s[20:21]
	global_load_lds_dwordx4 v144, s[20:21]
	s_barrier
	s_waitcnt lgkmcnt(0)
	v_mfma_f32_16x16x32_bf16 v[64:67], v[48:51], v[156:159], v[64:67]
	v_mfma_f32_16x16x32_bf16 v[60:63], v[72:75], v[156:159], v[60:63]
	v_mfma_f32_16x16x32_bf16 v[44:47], v[48:51], v[164:167], v[44:47]
	v_mfma_f32_16x16x32_bf16 v[40:43], v[72:75], v[164:167], v[40:43]
	v_mfma_f32_16x16x32_bf16 v[28:31], v[48:51], v[172:175], v[28:31]
	v_mfma_f32_16x16x32_bf16 v[24:27], v[72:75], v[172:175], v[24:27]
	v_mfma_f32_16x16x32_bf16 v[12:15], v[48:51], v[184:187], v[12:15]
	v_mfma_f32_16x16x32_bf16 v[8:11], v[72:75], v[184:187], v[8:11]
	v_mfma_f32_16x16x32_bf16 v[64:67], v[68:71], v[160:163], v[64:67]
	v_mfma_f32_16x16x32_bf16 v[60:63], v[76:79], v[160:163], v[60:63]
	v_mfma_f32_16x16x32_bf16 v[44:47], v[68:71], v[168:171], v[44:47]
	v_mfma_f32_16x16x32_bf16 v[40:43], v[76:79], v[168:171], v[40:43]
	v_mfma_f32_16x16x32_bf16 v[28:31], v[68:71], v[180:183], v[28:31]
	v_mfma_f32_16x16x32_bf16 v[24:27], v[76:79], v[180:183], v[24:27]
	v_mfma_f32_16x16x32_bf16 v[12:15], v[68:71], v[188:191], v[12:15]
	v_mfma_f32_16x16x32_bf16 v[8:11], v[76:79], v[188:191], v[8:11]
	s_barrier
	s_add_u32 s14, s18, 0x158000
	s_addc_u32 s15, s19, 0
	s_add_i32 s68, s69, s28
	s_mov_b32 m0, s68
	s_nop 0
	global_load_lds_dwordx4 v178, s[14:15]
	s_add_i32 m0, s68, 0x2000
	s_nop 0
	global_load_lds_dwordx4 v144, s[14:15]
	s_waitcnt vmcnt(6)
	s_barrier
	v_mfma_f32_16x16x32_bf16 v[52:55], v[204:207], v[156:159], v[52:55]
	v_mfma_f32_16x16x32_bf16 v[36:39], v[192:195], v[164:167], v[36:39]
	v_mfma_f32_16x16x32_bf16 v[32:35], v[204:207], v[164:167], v[32:35]
	v_mfma_f32_16x16x32_bf16 v[20:23], v[192:195], v[172:175], v[20:23]
	v_mfma_f32_16x16x32_bf16 v[16:19], v[204:207], v[172:175], v[16:19]
	v_mfma_f32_16x16x32_bf16 v[4:7], v[192:195], v[184:187], v[4:7]
	v_mfma_f32_16x16x32_bf16 v[0:3], v[204:207], v[184:187], v[0:3]
	v_mfma_f32_16x16x32_bf16 v[48:51], v[192:195], v[156:159], v[56:59]
	v_mfma_f32_16x16x32_bf16 v[52:55], v[212:215], v[160:163], v[52:55]
	v_mfma_f32_16x16x32_bf16 v[36:39], v[196:199], v[168:171], v[36:39]
	v_mfma_f32_16x16x32_bf16 v[32:35], v[212:215], v[168:171], v[32:35]
	v_mfma_f32_16x16x32_bf16 v[20:23], v[196:199], v[180:183], v[20:23]
	v_mfma_f32_16x16x32_bf16 v[16:19], v[212:215], v[180:183], v[16:19]
	v_mfma_f32_16x16x32_bf16 v[4:7], v[196:199], v[188:191], v[4:7]
	v_mfma_f32_16x16x32_bf16 v[0:3], v[212:215], v[188:191], v[0:3]
	v_mfma_f32_16x16x32_bf16 v[48:51], v[196:199], v[160:163], v[48:51]
	s_add_i32 s68, 0, 0x18000
	v_add_u32_e32 v76, s68, v153
	s_barrier
	ds_read_b128 v[56:59], v76
	ds_read_b128 v[68:71], v76 offset:1024
	ds_read_b128 v[72:75], v76 offset:2048
	ds_read_b128 v[76:79], v76 offset:3072
	s_add_u32 s14, s20, 0x158000
	s_addc_u32 s15, s21, 0
	s_mov_b32 m0, s31
	ds_read_b128 v[156:159], v155 offset:32768
	ds_read_b128 v[160:163], v155 offset:33792
	ds_read_b128 v[164:167], v155 offset:34816
	ds_read_b128 v[168:171], v155 offset:35840
	ds_read_b128 v[172:175], v155 offset:36864
	ds_read_b128 v[180:183], v155 offset:37888
	ds_read_b128 v[184:187], v155 offset:38912
	ds_read_b128 v[188:191], v155 offset:39936
	global_load_lds_dwordx4 v178, s[14:15]
	s_mov_b32 m0, s34
	s_nop 0
	global_load_lds_dwordx4 v144, s[14:15]
	s_waitcnt lgkmcnt(8)
	s_barrier
	s_waitcnt lgkmcnt(0)
	v_mfma_f32_16x16x32_bf16 v[140:143], v[56:59], v[156:159], v[140:143]
	v_mfma_f32_16x16x32_bf16 v[136:139], v[72:75], v[156:159], v[136:139]
	v_mfma_f32_16x16x32_bf16 v[124:127], v[56:59], v[164:167], v[124:127]
	v_mfma_f32_16x16x32_bf16 v[120:123], v[72:75], v[164:167], v[120:123]
	v_mfma_f32_16x16x32_bf16 v[116:119], v[56:59], v[172:175], v[116:119]
	v_mfma_f32_16x16x32_bf16 v[112:115], v[72:75], v[172:175], v[112:115]
	v_mfma_f32_16x16x32_bf16 v[100:103], v[56:59], v[184:187], v[100:103]
	v_mfma_f32_16x16x32_bf16 v[96:99], v[72:75], v[184:187], v[96:99]
	v_mfma_f32_16x16x32_bf16 v[140:143], v[68:71], v[160:163], v[140:143]
	v_mfma_f32_16x16x32_bf16 v[136:139], v[76:79], v[160:163], v[136:139]
	v_mfma_f32_16x16x32_bf16 v[124:127], v[68:71], v[168:171], v[124:127]
	v_mfma_f32_16x16x32_bf16 v[120:123], v[76:79], v[168:171], v[120:123]
	v_mfma_f32_16x16x32_bf16 v[116:119], v[68:71], v[180:183], v[116:119]
	v_mfma_f32_16x16x32_bf16 v[112:115], v[76:79], v[180:183], v[112:115]
	v_mfma_f32_16x16x32_bf16 v[100:103], v[68:71], v[188:191], v[100:103]
	v_mfma_f32_16x16x32_bf16 v[96:99], v[76:79], v[188:191], v[96:99]
	s_barrier
	s_add_i32 s20, 0, 0x1c000
	s_add_i32 s14, s68, s28
	v_add_u32_e32 v212, s20, v153
	s_add_i32 m0, s14, 0xffffff80
	ds_read_b128 v[192:195], v212
	ds_read_b128 v[196:199], v212 offset:1024
	ds_read_b128 v[204:207], v212 offset:2048
	ds_read_b128 v[212:215], v212 offset:3072
	global_load_lds_dwordx4 v178, s[18:19] offset:128
	s_add_i32 m0, s14, 0x1f80
	s_nop 0
	global_load_lds_dwordx4 v144, s[18:19] offset:128
	s_barrier
	s_waitcnt lgkmcnt(0)
	v_mfma_f32_16x16x32_bf16 v[132:135], v[192:195], v[156:159], v[132:135]
	v_mfma_f32_16x16x32_bf16 v[128:131], v[204:207], v[156:159], v[128:131]
	v_mfma_f32_16x16x32_bf16 v[108:111], v[192:195], v[164:167], v[108:111]
	v_mfma_f32_16x16x32_bf16 v[104:107], v[204:207], v[164:167], v[104:107]
	v_mfma_f32_16x16x32_bf16 v[92:95], v[192:195], v[172:175], v[92:95]
	v_mfma_f32_16x16x32_bf16 v[88:91], v[204:207], v[172:175], v[88:91]
	v_mfma_f32_16x16x32_bf16 v[84:87], v[192:195], v[184:187], v[84:87]
	v_mfma_f32_16x16x32_bf16 v[80:83], v[204:207], v[184:187], v[80:83]
	v_mfma_f32_16x16x32_bf16 v[132:135], v[196:199], v[160:163], v[132:135]
	v_mfma_f32_16x16x32_bf16 v[128:131], v[212:215], v[160:163], v[128:131]
	v_mfma_f32_16x16x32_bf16 v[108:111], v[196:199], v[168:171], v[108:111]
	v_mfma_f32_16x16x32_bf16 v[104:107], v[212:215], v[168:171], v[104:107]
	v_mfma_f32_16x16x32_bf16 v[92:95], v[196:199], v[180:183], v[92:95]
	v_mfma_f32_16x16x32_bf16 v[88:91], v[212:215], v[180:183], v[88:91]
	v_mfma_f32_16x16x32_bf16 v[84:87], v[196:199], v[188:191], v[84:87]
	v_mfma_f32_16x16x32_bf16 v[80:83], v[212:215], v[188:191], v[80:83]
	s_add_i32 m0, s56, 0xffffff80
	s_barrier
	ds_read_b128 v[156:159], v155 offset:49152
	ds_read_b128 v[160:163], v155 offset:50176
	ds_read_b128 v[164:167], v155 offset:51200
	ds_read_b128 v[168:171], v155 offset:52224
	ds_read_b128 v[172:175], v155 offset:53248
	ds_read_b128 v[180:183], v155 offset:54272
	ds_read_b128 v[184:187], v155 offset:55296
	ds_read_b128 v[188:191], v155 offset:56320
	global_load_lds_dwordx4 v178, s[100:101] offset:128
	s_add_i32 m0, s57, 0xffffff80
	s_nop 0
	global_load_lds_dwordx4 v144, s[100:101] offset:128
	s_barrier
	s_waitcnt lgkmcnt(0)
	v_mfma_f32_16x16x32_bf16 v[64:67], v[56:59], v[156:159], v[64:67]
	v_mfma_f32_16x16x32_bf16 v[60:63], v[72:75], v[156:159], v[60:63]
	v_mfma_f32_16x16x32_bf16 v[44:47], v[56:59], v[164:167], v[44:47]
	v_mfma_f32_16x16x32_bf16 v[40:43], v[72:75], v[164:167], v[40:43]
	v_mfma_f32_16x16x32_bf16 v[28:31], v[56:59], v[172:175], v[28:31]
	v_mfma_f32_16x16x32_bf16 v[24:27], v[72:75], v[172:175], v[24:27]
	v_mfma_f32_16x16x32_bf16 v[12:15], v[56:59], v[184:187], v[12:15]
	v_mfma_f32_16x16x32_bf16 v[8:11], v[72:75], v[184:187], v[8:11]
	v_mfma_f32_16x16x32_bf16 v[64:67], v[68:71], v[160:163], v[64:67]
	v_mfma_f32_16x16x32_bf16 v[60:63], v[76:79], v[160:163], v[60:63]
	v_mfma_f32_16x16x32_bf16 v[44:47], v[68:71], v[168:171], v[44:47]
	v_mfma_f32_16x16x32_bf16 v[40:43], v[76:79], v[168:171], v[40:43]
	v_mfma_f32_16x16x32_bf16 v[28:31], v[68:71], v[180:183], v[28:31]
	v_mfma_f32_16x16x32_bf16 v[24:27], v[76:79], v[180:183], v[24:27]
	v_mfma_f32_16x16x32_bf16 v[12:15], v[68:71], v[188:191], v[12:15]
	v_mfma_f32_16x16x32_bf16 v[8:11], v[76:79], v[188:191], v[8:11]
	s_barrier
	s_add_u32 s14, s18, 0x158080
	s_addc_u32 s15, s19, 0
	s_add_i32 s18, s20, s28
	s_mov_b32 m0, s18
	s_nop 0
	global_load_lds_dwordx4 v178, s[14:15]
	s_add_i32 m0, s18, 0x2000
	s_nop 0
	global_load_lds_dwordx4 v144, s[14:15]
	s_waitcnt vmcnt(6)
	s_barrier
	v_mfma_f32_16x16x32_bf16 v[48:51], v[192:195], v[156:159], v[48:51]
	v_mfma_f32_16x16x32_bf16 v[56:59], v[196:199], v[160:163], v[48:51]
	v_mfma_f32_16x16x32_bf16 v[48:51], v[204:207], v[156:159], v[52:55]
	v_mfma_f32_16x16x32_bf16 v[36:39], v[192:195], v[164:167], v[36:39]
	v_mfma_f32_16x16x32_bf16 v[32:35], v[204:207], v[164:167], v[32:35]
	v_mfma_f32_16x16x32_bf16 v[20:23], v[192:195], v[172:175], v[20:23]
	v_mfma_f32_16x16x32_bf16 v[16:19], v[204:207], v[172:175], v[16:19]
	v_mfma_f32_16x16x32_bf16 v[4:7], v[192:195], v[184:187], v[4:7]
	v_mfma_f32_16x16x32_bf16 v[0:3], v[204:207], v[184:187], v[0:3]
	v_mfma_f32_16x16x32_bf16 v[52:55], v[212:215], v[160:163], v[48:51]
	v_mfma_f32_16x16x32_bf16 v[36:39], v[196:199], v[168:171], v[36:39]
	v_mfma_f32_16x16x32_bf16 v[32:35], v[212:215], v[168:171], v[32:35]
	v_mfma_f32_16x16x32_bf16 v[20:23], v[196:199], v[180:183], v[20:23]
	v_mfma_f32_16x16x32_bf16 v[16:19], v[212:215], v[180:183], v[16:19]
	v_mfma_f32_16x16x32_bf16 v[4:7], v[196:199], v[188:191], v[4:7]
	v_mfma_f32_16x16x32_bf16 v[0:3], v[212:215], v[188:191], v[0:3]
	s_add_i32 s67, s67, 2
	s_add_u32 s63, s63, 0x100
	s_addc_u32 s66, s66, 0
	s_cmpk_gt_u32 s67, 0x53
	s_mov_b64 s[14:15], s[16:17]
	s_barrier
	s_cbranch_scc0 .LBB0_1363
	s_lshl_b32 s12, s61, 8
	s_add_i32 s10, s12, 0xfffff000
	s_ashr_i32 s10, s10, 11
	s_add_i32 s10, s10, 1
	s_cmp_gt_i32 s61, 15
	s_cselect_b32 s10, s10, 0
	v_add_u32_e32 v162, s12, v152
	v_lshl_or_b32 v48, s62, 8, v154
	s_mul_hi_i32 s11, s10, 0xc000
	s_mul_i32 s10, s10, 0xc000
	v_ashrrev_i32_e32 v163, 31, v162
	v_readlane_b32 s68, v252, 37
	s_add_u32 s10, s35, s10
	v_ashrrev_i32_e32 v49, 31, v48
	v_lshlrev_b64 v[150:151], 13, v[162:163]
	v_readlane_b32 s82, v252, 51
	v_readlane_b32 s83, v252, 52
	s_addc_u32 s11, s39, s11
	v_lshlrev_b64 v[160:161], 2, v[48:49]
	v_lshl_add_u64 v[150:151], s[82:83], 0, v[150:151]
	v_lshl_add_u64 v[48:49], s[10:11], 0, v[160:161]
	v_lshl_add_u64 v[150:151], v[150:151], 0, v[160:161]
	global_load_dwordx4 v[76:79], v[48:49], off
	global_load_dwordx4 v[72:75], v[48:49], off offset:64
	global_load_dwordx4 v[68:71], v[48:49], off offset:512
	s_nop 0
	global_load_dwordx4 v[48:51], v[48:49], off offset:576
	s_mov_b64 s[10:11], 0x100000
	s_mov_b32 s62, s59
	s_mov_b32 s61, s60
	s_mov_b64 s[16:17], s[6:7]
	s_mov_b64 s[14:15], s[8:9]
	v_readlane_b32 s69, v252, 38
	v_readlane_b32 s70, v252, 39
	v_readlane_b32 s71, v252, 40
	v_readlane_b32 s72, v252, 41
	v_readlane_b32 s73, v252, 42
	v_readlane_b32 s74, v252, 43
	v_readlane_b32 s75, v252, 44
	v_readlane_b32 s76, v252, 45
	v_readlane_b32 s77, v252, 46
	v_readlane_b32 s78, v252, 47
	v_readlane_b32 s79, v252, 48
	v_readlane_b32 s80, v252, 49
	v_readlane_b32 s81, v252, 50
	s_and_b64 vcc, exec, s[4:5]
	s_nop 4
	v_lshl_add_u32 v145, v162, 13, v160
	v_add_u32_e32 v156, 0x20000, v145
	v_add_u32_e32 v158, 0x40000, v145
	v_add_u32_e32 v159, 0x60000, v145
	v_add_u32_e32 v176, 0x100000, v145
	v_add_u32_e32 v177, 0x120000, v145
	v_add_u32_e32 v223, 0x140000, v145
	v_add_u32_e32 v248, 0x160000, v145
	global_load_dwordx4 v[164:167], v145, s[82:83]
	global_load_dwordx4 v[168:171], v145, s[82:83] offset:64
	global_load_dwordx4 v[172:175], v145, s[82:83] offset:512
	global_load_dwordx4 v[180:183], v145, s[82:83] offset:576
	global_load_dwordx4 v[184:187], v156, s[82:83]
	global_load_dwordx4 v[188:191], v156, s[82:83] offset:64
	global_load_dwordx4 v[192:195], v156, s[82:83] offset:512
	global_load_dwordx4 v[196:199], v156, s[82:83] offset:576
	global_load_dwordx4 v[204:207], v158, s[82:83]
	global_load_dwordx4 v[212:215], v158, s[82:83] offset:64
	global_load_dwordx4 v[224:227], v158, s[82:83] offset:512
	global_load_dwordx4 v[228:231], v158, s[82:83] offset:576
	global_load_dwordx4 v[232:235], v159, s[82:83]
	global_load_dwordx4 v[236:239], v159, s[82:83] offset:64
	global_load_dwordx4 v[240:243], v159, s[82:83] offset:512
	global_load_dwordx4 v[244:247], v159, s[82:83] offset:576
	s_waitcnt vmcnt(15)
	v_pk_fma_f32 v[142:143], v[142:143], v[78:79], v[166:167]
	v_pk_fma_f32 v[140:141], v[140:141], v[76:77], v[164:165]
	global_store_dwordx4 v145, v[140:143], s[82:83]
	global_load_dwordx4 v[164:167], v176, s[82:83]
	s_waitcnt vmcnt(16)
	v_pk_fma_f32 v[138:139], v[138:139], v[74:75], v[170:171]
	v_pk_fma_f32 v[136:137], v[136:137], v[72:73], v[168:169]
	global_store_dwordx4 v145, v[136:139], s[82:83] offset:64
	global_load_dwordx4 v[168:171], v176, s[82:83] offset:64
	s_waitcnt vmcnt(17)
	v_pk_fma_f32 v[134:135], v[134:135], v[70:71], v[174:175]
	v_pk_fma_f32 v[132:133], v[132:133], v[68:69], v[172:173]
	global_store_dwordx4 v145, v[132:135], s[82:83] offset:512
	global_load_dwordx4 v[172:175], v176, s[82:83] offset:512
	s_waitcnt vmcnt(18)
	v_pk_fma_f32 v[130:131], v[130:131], v[50:51], v[182:183]
	v_pk_fma_f32 v[128:129], v[128:129], v[48:49], v[180:181]
	global_store_dwordx4 v145, v[128:131], s[82:83] offset:576
	global_load_dwordx4 v[180:183], v176, s[82:83] offset:576
	s_waitcnt vmcnt(19)
	v_pk_fma_f32 v[126:127], v[126:127], v[78:79], v[186:187]
	v_pk_fma_f32 v[124:125], v[124:125], v[76:77], v[184:185]
	global_store_dwordx4 v156, v[124:127], s[82:83]
	global_load_dwordx4 v[184:187], v177, s[82:83]
	s_waitcnt vmcnt(20)
	v_pk_fma_f32 v[122:123], v[122:123], v[74:75], v[190:191]
	v_pk_fma_f32 v[120:121], v[120:121], v[72:73], v[188:189]
	global_store_dwordx4 v156, v[120:123], s[82:83] offset:64
	global_load_dwordx4 v[188:191], v177, s[82:83] offset:64
	s_waitcnt vmcnt(21)
	v_pk_fma_f32 v[110:111], v[110:111], v[70:71], v[194:195]
	v_pk_fma_f32 v[108:109], v[108:109], v[68:69], v[192:193]
	global_store_dwordx4 v156, v[108:111], s[82:83] offset:512
	global_load_dwordx4 v[192:195], v177, s[82:83] offset:512
	s_waitcnt vmcnt(22)
	v_pk_fma_f32 v[106:107], v[106:107], v[50:51], v[198:199]
	v_pk_fma_f32 v[104:105], v[104:105], v[48:49], v[196:197]
	global_store_dwordx4 v156, v[104:107], s[82:83] offset:576
	global_load_dwordx4 v[196:199], v177, s[82:83] offset:576
	s_waitcnt vmcnt(23)
	v_pk_fma_f32 v[118:119], v[118:119], v[78:79], v[206:207]
	v_pk_fma_f32 v[116:117], v[116:117], v[76:77], v[204:205]
	global_store_dwordx4 v158, v[116:119], s[82:83]
	global_load_dwordx4 v[204:207], v223, s[82:83]
	s_waitcnt vmcnt(24)
	v_pk_fma_f32 v[114:115], v[114:115], v[74:75], v[214:215]
	v_pk_fma_f32 v[112:113], v[112:113], v[72:73], v[212:213]
	global_store_dwordx4 v158, v[112:115], s[82:83] offset:64
	global_load_dwordx4 v[212:215], v223, s[82:83] offset:64
	s_waitcnt vmcnt(25)
	v_pk_fma_f32 v[94:95], v[94:95], v[70:71], v[226:227]
	v_pk_fma_f32 v[92:93], v[92:93], v[68:69], v[224:225]
	global_store_dwordx4 v158, v[92:95], s[82:83] offset:512
	global_load_dwordx4 v[224:227], v223, s[82:83] offset:512
	s_waitcnt vmcnt(26)
	v_pk_fma_f32 v[90:91], v[90:91], v[50:51], v[230:231]
	v_pk_fma_f32 v[88:89], v[88:89], v[48:49], v[228:229]
	global_store_dwordx4 v158, v[88:91], s[82:83] offset:576
	global_load_dwordx4 v[228:231], v223, s[82:83] offset:576
	s_waitcnt vmcnt(27)
	v_pk_fma_f32 v[102:103], v[102:103], v[78:79], v[234:235]
	v_pk_fma_f32 v[100:101], v[100:101], v[76:77], v[232:233]
	global_store_dwordx4 v159, v[100:103], s[82:83]
	global_load_dwordx4 v[232:235], v248, s[82:83]
	s_waitcnt vmcnt(28)
	v_pk_fma_f32 v[98:99], v[98:99], v[74:75], v[238:239]
	v_pk_fma_f32 v[96:97], v[96:97], v[72:73], v[236:237]
	global_store_dwordx4 v159, v[96:99], s[82:83] offset:64
	global_load_dwordx4 v[236:239], v248, s[82:83] offset:64
	s_waitcnt vmcnt(29)
	v_pk_fma_f32 v[86:87], v[86:87], v[70:71], v[242:243]
	v_pk_fma_f32 v[84:85], v[84:85], v[68:69], v[240:241]
	global_store_dwordx4 v159, v[84:87], s[82:83] offset:512
	global_load_dwordx4 v[240:243], v248, s[82:83] offset:512
	s_waitcnt vmcnt(30)
	v_pk_fma_f32 v[82:83], v[82:83], v[50:51], v[246:247]
	v_pk_fma_f32 v[80:81], v[80:81], v[48:49], v[244:245]
	global_store_dwordx4 v159, v[80:83], s[82:83] offset:576
	global_load_dwordx4 v[244:247], v248, s[82:83] offset:576
	s_waitcnt vmcnt(30)
	v_pk_fma_f32 v[66:67], v[66:67], v[78:79], v[166:167]
	v_pk_fma_f32 v[64:65], v[64:65], v[76:77], v[164:165]
	global_store_dwordx4 v176, v[64:67], s[82:83]
	s_waitcnt vmcnt(29)
	v_pk_fma_f32 v[62:63], v[62:63], v[74:75], v[170:171]
	v_pk_fma_f32 v[60:61], v[60:61], v[72:73], v[168:169]
	global_store_dwordx4 v176, v[60:63], s[82:83] offset:64
	s_waitcnt vmcnt(28)
	v_pk_fma_f32 v[58:59], v[58:59], v[70:71], v[174:175]
	v_pk_fma_f32 v[56:57], v[56:57], v[68:69], v[172:173]
	global_store_dwordx4 v176, v[56:59], s[82:83] offset:512
	s_waitcnt vmcnt(27)
	v_pk_fma_f32 v[54:55], v[54:55], v[50:51], v[182:183]
	v_pk_fma_f32 v[52:53], v[52:53], v[48:49], v[180:181]
	global_store_dwordx4 v176, v[52:55], s[82:83] offset:576
	s_waitcnt vmcnt(26)
	v_pk_fma_f32 v[46:47], v[46:47], v[78:79], v[186:187]
	v_pk_fma_f32 v[44:45], v[44:45], v[76:77], v[184:185]
	global_store_dwordx4 v177, v[44:47], s[82:83]
	s_waitcnt vmcnt(25)
	v_pk_fma_f32 v[42:43], v[42:43], v[74:75], v[190:191]
	v_pk_fma_f32 v[40:41], v[40:41], v[72:73], v[188:189]
	global_store_dwordx4 v177, v[40:43], s[82:83] offset:64
	s_waitcnt vmcnt(24)
	v_pk_fma_f32 v[38:39], v[38:39], v[70:71], v[194:195]
	v_pk_fma_f32 v[36:37], v[36:37], v[68:69], v[192:193]
	global_store_dwordx4 v177, v[36:39], s[82:83] offset:512
	s_waitcnt vmcnt(23)
	v_pk_fma_f32 v[34:35], v[34:35], v[50:51], v[198:199]
	v_pk_fma_f32 v[32:33], v[32:33], v[48:49], v[196:197]
	global_store_dwordx4 v177, v[32:35], s[82:83] offset:576
	s_waitcnt vmcnt(22)
	v_pk_fma_f32 v[30:31], v[30:31], v[78:79], v[206:207]
	v_pk_fma_f32 v[28:29], v[28:29], v[76:77], v[204:205]
	global_store_dwordx4 v223, v[28:31], s[82:83]
	s_waitcnt vmcnt(21)
	v_pk_fma_f32 v[26:27], v[26:27], v[74:75], v[214:215]
	v_pk_fma_f32 v[24:25], v[24:25], v[72:73], v[212:213]
	global_store_dwordx4 v223, v[24:27], s[82:83] offset:64
	s_waitcnt vmcnt(20)
	v_pk_fma_f32 v[22:23], v[22:23], v[70:71], v[226:227]
	v_pk_fma_f32 v[20:21], v[20:21], v[68:69], v[224:225]
	global_store_dwordx4 v223, v[20:23], s[82:83] offset:512
	s_waitcnt vmcnt(19)
	v_pk_fma_f32 v[18:19], v[18:19], v[50:51], v[230:231]
	v_pk_fma_f32 v[16:17], v[16:17], v[48:49], v[228:229]
	global_store_dwordx4 v223, v[16:19], s[82:83] offset:576
	s_waitcnt vmcnt(18)
	v_pk_fma_f32 v[14:15], v[14:15], v[78:79], v[234:235]
	v_pk_fma_f32 v[12:13], v[12:13], v[76:77], v[232:233]
	global_store_dwordx4 v248, v[12:15], s[82:83]
	s_waitcnt vmcnt(17)
	v_pk_fma_f32 v[10:11], v[10:11], v[74:75], v[238:239]
	v_pk_fma_f32 v[8:9], v[8:9], v[72:73], v[236:237]
	global_store_dwordx4 v248, v[8:11], s[82:83] offset:64
	s_waitcnt vmcnt(16)
	v_pk_fma_f32 v[6:7], v[6:7], v[70:71], v[242:243]
	v_pk_fma_f32 v[4:5], v[4:5], v[68:69], v[240:241]
	global_store_dwordx4 v248, v[4:7], s[82:83] offset:512
	s_waitcnt vmcnt(15)
	v_pk_fma_f32 v[2:3], v[2:3], v[50:51], v[246:247]
	v_pk_fma_f32 v[0:1], v[0:1], v[48:49], v[244:245]
	global_store_dwordx4 v248, v[0:3], s[82:83] offset:576
	s_mov_b64 s[10:11], 0x160000
	s_cbranch_vccz .LBB0_1360
	s_waitcnt vmcnt(0)
	s_mov_b32 s4, s86
	s_cmp_gt_u32 s4, 3
	s_movk_i32 s57, 0x404
	s_cbranch_scc1 .LBB0_1367
	s_barrier
